# baseline (speedup 1.0000x reference)
; DEVI void rwkv_scan_item(const Params& p, const int item, char* smem) {
;     ...
;   for (int c = 0; c < NC; ++c) {
;     if (wid >= 4) {
;       if (c + 1 < NC) load_chunk(c + 1, (c + 1) & 1);
;       if (c >= 1) store_y(c - 1);
;     } else {
;       const float* sb = buf + (c & 1) * 12288 + kp * 4;
;       float* yb = ybuf + (c & 1) * 2048 + row16 * 4 + (kp >> 2);
;       const int vofs = 320 + rq * 16 + row16 - kp * 4;
;       f32x4 kkA, wA, kaA, kA, rA, kkB, wB, kaB, kB, rB; float vA, vB;
;       RW_LD(0, A)
; #pragma unroll 2
;       for (int s = 0; s < 32; s += 2) {
;         RW_LD(s + 1, B)
;         __builtin_amdgcn_sched_barrier(0);
;         RW_STEP(s, A)
;         __builtin_amdgcn_sched_barrier(0);
;         if (s + 2 < 32) RW_LD(s + 2, A)
;         __builtin_amdgcn_sched_barrier(0);
;         RW_STEP(s + 1, B)
;         __builtin_amdgcn_sched_barrier(0);
;       }
.LBB0_514:
	s_and_saveexec_b64 s[64:65], s[2:3]
	s_xor_b64 s[64:65], exec, s[64:65]
	s_cbranch_execz .LBB0_519
	s_setprio 3
	s_and_b32 s58, s78, 1
	s_mul_i32 s58, s58, 0xc000
	v_add_u32_e32 v98, s58, v81
	ds_read_b128 v[2:5], v98
	v_lshl_add_u32 v99, v63, 2, v98
	ds_read_b32 v22, v99 offset:1280
	ds_read_b128 v[14:17], v98 offset:768
	ds_read_b128 v[6:9], v98 offset:256
	ds_read_b128 v[10:13], v98 offset:512
	ds_read_b128 v[18:21], v98 offset:1024
	s_and_b32 s58, s78, 1
	s_lshl_b32 s58, s58, 13
	s_add_i32 s58, s58, 0x18010
	v_add_u32_e32 v97, s58, v93
	s_waitcnt lgkmcnt(0)
	v_pk_mul_f32 v[104:105], v[100:101], v[2:3]
	s_nop 0
	v_pk_fma_f32 v[104:105], v[102:103], v[4:5], v[104:105]
	s_nop 0
	v_add_f32_e32 v104, v104, v105
	ds_read_b32 v40, v99 offset:2816
	ds_read_b128 v[36:39], v98 offset:2304
	v_add_f32_dpp v104, v104, v104 quad_perm:[1,0,3,2] row_mask:0xf bank_mask:0xf bound_ctrl:1
	ds_read_b128 v[24:27], v98 offset:1536
	ds_read_b128 v[28:31], v98 offset:1792
	v_add_f32_dpp v104, v104, v104 quad_perm:[2,3,0,1] row_mask:0xf bank_mask:0xf bound_ctrl:1
	v_pk_mul_f32 v[14:15], v[14:15], v[22:23] op_sel_hi:[1,0]
	v_pk_mul_f32 v[16:17], v[16:17], v[22:23] op_sel_hi:[1,0]
	v_add_f32_dpp v104, v104, v104 row_half_mirror row_mask:0xf bank_mask:0xf bound_ctrl:1
	s_waitcnt lgkmcnt(5)
	v_pk_fma_f32 v[14:15], v[100:101], v[6:7], v[14:15]
	v_pk_fma_f32 v[16:17], v[102:103], v[8:9], v[16:17]
	v_add_f32_dpp v104, v104, v104 row_mirror row_mask:0xf bank_mask:0xf bound_ctrl:1
	v_pk_fma_f32 v[100:101], v[10:11], v[104:105], v[14:15] op_sel_hi:[1,0,1] neg_lo:[0,1,0] neg_hi:[0,1,0]
	v_pk_fma_f32 v[102:103], v[12:13], v[104:105], v[16:17] op_sel_hi:[1,0,1] neg_lo:[0,1,0] neg_hi:[0,1,0]
	v_pk_mul_f32 v[106:107], v[100:101], v[18:19]
	ds_read_b128 v[32:35], v98 offset:2048
	v_pk_fma_f32 v[106:107], v[102:103], v[20:21], v[106:107]
	s_waitcnt lgkmcnt(2)
	v_pk_mul_f32 v[104:105], v[100:101], v[24:25]
	v_add_f32_e32 v106, v106, v107
	ds_read_b128 v[84:87], v98 offset:2560
	v_pk_fma_f32 v[104:105], v[102:103], v[26:27], v[104:105]
	v_add_f32_dpp v106, v106, v106 quad_perm:[1,0,3,2] row_mask:0xf bank_mask:0xf bound_ctrl:1
	v_add_f32_e32 v104, v104, v105
	s_nop 0
	v_add_f32_dpp v106, v106, v106 quad_perm:[2,3,0,1] row_mask:0xf bank_mask:0xf bound_ctrl:1
	ds_write_b32 v97, v106 offset:0
	ds_read_b32 v22, v99 offset:4352
	ds_read_b128 v[14:17], v98 offset:3840
	v_add_f32_dpp v104, v104, v104 quad_perm:[1,0,3,2] row_mask:0xf bank_mask:0xf bound_ctrl:1
	ds_read_b128 v[2:5], v98 offset:3072
	ds_read_b128 v[6:9], v98 offset:3328
	v_add_f32_dpp v104, v104, v104 quad_perm:[2,3,0,1] row_mask:0xf bank_mask:0xf bound_ctrl:1
	v_pk_mul_f32 v[36:37], v[36:37], v[40:41] op_sel_hi:[1,0]
	v_pk_mul_f32 v[38:39], v[38:39], v[40:41] op_sel_hi:[1,0]
	v_add_f32_dpp v104, v104, v104 row_half_mirror row_mask:0xf bank_mask:0xf bound_ctrl:1
	s_waitcnt lgkmcnt(5)
	v_pk_fma_f32 v[36:37], v[100:101], v[28:29], v[36:37]
	v_pk_fma_f32 v[38:39], v[102:103], v[30:31], v[38:39]
	v_add_f32_dpp v104, v104, v104 row_mirror row_mask:0xf bank_mask:0xf bound_ctrl:1
	v_pk_fma_f32 v[100:101], v[32:33], v[104:105], v[36:37] op_sel_hi:[1,0,1] neg_lo:[0,1,0] neg_hi:[0,1,0]
	v_pk_fma_f32 v[102:103], v[34:35], v[104:105], v[38:39] op_sel_hi:[1,0,1] neg_lo:[0,1,0] neg_hi:[0,1,0]
	v_pk_mul_f32 v[106:107], v[100:101], v[84:85]
	ds_read_b128 v[10:13], v98 offset:3584
	v_pk_fma_f32 v[106:107], v[102:103], v[86:87], v[106:107]
	s_waitcnt lgkmcnt(2)
	v_pk_mul_f32 v[104:105], v[100:101], v[2:3]
	v_add_f32_e32 v106, v106, v107
	ds_read_b128 v[18:21], v98 offset:4096
	v_pk_fma_f32 v[104:105], v[102:103], v[4:5], v[104:105]
	v_add_f32_dpp v106, v106, v106 quad_perm:[1,0,3,2] row_mask:0xf bank_mask:0xf bound_ctrl:1
	v_add_f32_e32 v104, v104, v105
	s_nop 0
	v_add_f32_dpp v106, v106, v106 quad_perm:[2,3,0,1] row_mask:0xf bank_mask:0xf bound_ctrl:1
	ds_write_b32 v97, v106 offset:256
	ds_read_b32 v40, v99 offset:5888
	ds_read_b128 v[36:39], v98 offset:5376
	v_add_f32_dpp v104, v104, v104 quad_perm:[1,0,3,2] row_mask:0xf bank_mask:0xf bound_ctrl:1
	ds_read_b128 v[24:27], v98 offset:4608
	ds_read_b128 v[28:31], v98 offset:4864
	v_add_f32_dpp v104, v104, v104 quad_perm:[2,3,0,1] row_mask:0xf bank_mask:0xf bound_ctrl:1
	v_pk_mul_f32 v[14:15], v[14:15], v[22:23] op_sel_hi:[1,0]
	v_pk_mul_f32 v[16:17], v[16:17], v[22:23] op_sel_hi:[1,0]
	v_add_f32_dpp v104, v104, v104 row_half_mirror row_mask:0xf bank_mask:0xf bound_ctrl:1
	s_waitcnt lgkmcnt(5)
	v_pk_fma_f32 v[14:15], v[100:101], v[6:7], v[14:15]
	v_pk_fma_f32 v[16:17], v[102:103], v[8:9], v[16:17]
	v_add_f32_dpp v104, v104, v104 row_mirror row_mask:0xf bank_mask:0xf bound_ctrl:1
	v_pk_fma_f32 v[100:101], v[10:11], v[104:105], v[14:15] op_sel_hi:[1,0,1] neg_lo:[0,1,0] neg_hi:[0,1,0]
	v_pk_fma_f32 v[102:103], v[12:13], v[104:105], v[16:17] op_sel_hi:[1,0,1] neg_lo:[0,1,0] neg_hi:[0,1,0]
	v_pk_mul_f32 v[106:107], v[100:101], v[18:19]
	ds_read_b128 v[32:35], v98 offset:5120
	v_pk_fma_f32 v[106:107], v[102:103], v[20:21], v[106:107]
	s_waitcnt lgkmcnt(2)
	v_pk_mul_f32 v[104:105], v[100:101], v[24:25]
	v_add_f32_e32 v106, v106, v107
	ds_read_b128 v[84:87], v98 offset:5632
	v_pk_fma_f32 v[104:105], v[102:103], v[26:27], v[104:105]
	v_add_f32_dpp v106, v106, v106 quad_perm:[1,0,3,2] row_mask:0xf bank_mask:0xf bound_ctrl:1
	v_add_f32_e32 v104, v104, v105
	s_nop 0
	v_add_f32_dpp v106, v106, v106 quad_perm:[2,3,0,1] row_mask:0xf bank_mask:0xf bound_ctrl:1
	ds_write_b32 v97, v106 offset:512
	ds_read_b32 v22, v99 offset:7424
	ds_read_b128 v[14:17], v98 offset:6912
	v_add_f32_dpp v104, v104, v104 quad_perm:[1,0,3,2] row_mask:0xf bank_mask:0xf bound_ctrl:1
	ds_read_b128 v[2:5], v98 offset:6144
	ds_read_b128 v[6:9], v98 offset:6400
	v_add_f32_dpp v104, v104, v104 quad_perm:[2,3,0,1] row_mask:0xf bank_mask:0xf bound_ctrl:1
	v_pk_mul_f32 v[36:37], v[36:37], v[40:41] op_sel_hi:[1,0]
	v_pk_mul_f32 v[38:39], v[38:39], v[40:41] op_sel_hi:[1,0]
	v_add_f32_dpp v104, v104, v104 row_half_mirror row_mask:0xf bank_mask:0xf bound_ctrl:1
	s_waitcnt lgkmcnt(5)
; DEVI void rwkv_scan_item(const Params& p, const int item, char* smem) {
;     ...
;   for (int c = 0; c < NC; ++c) {
;     if (wid >= 4) {
;       if (c + 1 < NC) load_chunk(c + 1, (c + 1) & 1);
;       if (c >= 1) store_y(c - 1);
;     } else {
;       const float* sb = buf + (c & 1) * 12288 + kp * 4;
;       float* yb = ybuf + (c & 1) * 2048 + row16 * 4 + (kp >> 2);
;       const int vofs = 320 + rq * 16 + row16 - kp * 4;
;       f32x4 kkA, wA, kaA, kA, rA, kkB, wB, kaB, kB, rB; float vA, vB;
;       RW_LD(0, A)
; #pragma unroll 2
;       for (int s = 0; s < 32; s += 2) {
;         RW_LD(s + 1, B)
;         __builtin_amdgcn_sched_barrier(0);
;         RW_STEP(s, A)
;         __builtin_amdgcn_sched_barrier(0);
;         if (s + 2 < 32) RW_LD(s + 2, A)
;         __builtin_amdgcn_sched_barrier(0);
;         RW_STEP(s + 1, B)
;         __builtin_amdgcn_sched_barrier(0);
;       }
	v_pk_fma_f32 v[36:37], v[100:101], v[28:29], v[36:37]
	v_pk_fma_f32 v[38:39], v[102:103], v[30:31], v[38:39]
	v_add_f32_dpp v104, v104, v104 row_mirror row_mask:0xf bank_mask:0xf bound_ctrl:1
	v_pk_fma_f32 v[100:101], v[32:33], v[104:105], v[36:37] op_sel_hi:[1,0,1] neg_lo:[0,1,0] neg_hi:[0,1,0]
	v_pk_fma_f32 v[102:103], v[34:35], v[104:105], v[38:39] op_sel_hi:[1,0,1] neg_lo:[0,1,0] neg_hi:[0,1,0]
	v_pk_mul_f32 v[106:107], v[100:101], v[84:85]
	ds_read_b128 v[10:13], v98 offset:6656
	v_pk_fma_f32 v[106:107], v[102:103], v[86:87], v[106:107]
	s_waitcnt lgkmcnt(2)
	v_pk_mul_f32 v[104:105], v[100:101], v[2:3]
	v_add_f32_e32 v106, v106, v107
	ds_read_b128 v[18:21], v98 offset:7168
	v_pk_fma_f32 v[104:105], v[102:103], v[4:5], v[104:105]
	v_add_f32_dpp v106, v106, v106 quad_perm:[1,0,3,2] row_mask:0xf bank_mask:0xf bound_ctrl:1
	v_add_f32_e32 v104, v104, v105
	s_nop 0
	v_add_f32_dpp v106, v106, v106 quad_perm:[2,3,0,1] row_mask:0xf bank_mask:0xf bound_ctrl:1
	ds_write_b32 v97, v106 offset:768
	ds_read_b32 v40, v99 offset:8960
	ds_read_b128 v[36:39], v98 offset:8448
	v_add_f32_dpp v104, v104, v104 quad_perm:[1,0,3,2] row_mask:0xf bank_mask:0xf bound_ctrl:1
	ds_read_b128 v[24:27], v98 offset:7680
	ds_read_b128 v[28:31], v98 offset:7936
	v_add_f32_dpp v104, v104, v104 quad_perm:[2,3,0,1] row_mask:0xf bank_mask:0xf bound_ctrl:1
	v_pk_mul_f32 v[14:15], v[14:15], v[22:23] op_sel_hi:[1,0]
	v_pk_mul_f32 v[16:17], v[16:17], v[22:23] op_sel_hi:[1,0]
	v_add_f32_dpp v104, v104, v104 row_half_mirror row_mask:0xf bank_mask:0xf bound_ctrl:1
	s_waitcnt lgkmcnt(5)
	v_pk_fma_f32 v[14:15], v[100:101], v[6:7], v[14:15]
	v_pk_fma_f32 v[16:17], v[102:103], v[8:9], v[16:17]
	v_add_f32_dpp v104, v104, v104 row_mirror row_mask:0xf bank_mask:0xf bound_ctrl:1
	v_pk_fma_f32 v[100:101], v[10:11], v[104:105], v[14:15] op_sel_hi:[1,0,1] neg_lo:[0,1,0] neg_hi:[0,1,0]
	v_pk_fma_f32 v[102:103], v[12:13], v[104:105], v[16:17] op_sel_hi:[1,0,1] neg_lo:[0,1,0] neg_hi:[0,1,0]
	v_pk_mul_f32 v[106:107], v[100:101], v[18:19]
	ds_read_b128 v[32:35], v98 offset:8192
	v_pk_fma_f32 v[106:107], v[102:103], v[20:21], v[106:107]
	s_waitcnt lgkmcnt(2)
	v_pk_mul_f32 v[104:105], v[100:101], v[24:25]
	v_add_f32_e32 v106, v106, v107
	ds_read_b128 v[84:87], v98 offset:8704
	v_pk_fma_f32 v[104:105], v[102:103], v[26:27], v[104:105]
	v_add_f32_dpp v106, v106, v106 quad_perm:[1,0,3,2] row_mask:0xf bank_mask:0xf bound_ctrl:1
	v_add_f32_e32 v104, v104, v105
	s_nop 0
	v_add_f32_dpp v106, v106, v106 quad_perm:[2,3,0,1] row_mask:0xf bank_mask:0xf bound_ctrl:1
	ds_write_b32 v97, v106 offset:1024
	ds_read_b32 v22, v99 offset:10496
	ds_read_b128 v[14:17], v98 offset:9984
	v_add_f32_dpp v104, v104, v104 quad_perm:[1,0,3,2] row_mask:0xf bank_mask:0xf bound_ctrl:1
	ds_read_b128 v[2:5], v98 offset:9216
	ds_read_b128 v[6:9], v98 offset:9472
	v_add_f32_dpp v104, v104, v104 quad_perm:[2,3,0,1] row_mask:0xf bank_mask:0xf bound_ctrl:1
	v_pk_mul_f32 v[36:37], v[36:37], v[40:41] op_sel_hi:[1,0]
	v_pk_mul_f32 v[38:39], v[38:39], v[40:41] op_sel_hi:[1,0]
	v_add_f32_dpp v104, v104, v104 row_half_mirror row_mask:0xf bank_mask:0xf bound_ctrl:1
	s_waitcnt lgkmcnt(5)
	v_pk_fma_f32 v[36:37], v[100:101], v[28:29], v[36:37]
	v_pk_fma_f32 v[38:39], v[102:103], v[30:31], v[38:39]
	v_add_f32_dpp v104, v104, v104 row_mirror row_mask:0xf bank_mask:0xf bound_ctrl:1
	v_pk_fma_f32 v[100:101], v[32:33], v[104:105], v[36:37] op_sel_hi:[1,0,1] neg_lo:[0,1,0] neg_hi:[0,1,0]
	v_pk_fma_f32 v[102:103], v[34:35], v[104:105], v[38:39] op_sel_hi:[1,0,1] neg_lo:[0,1,0] neg_hi:[0,1,0]
	v_pk_mul_f32 v[106:107], v[100:101], v[84:85]
	ds_read_b128 v[10:13], v98 offset:9728
	v_pk_fma_f32 v[106:107], v[102:103], v[86:87], v[106:107]
	s_waitcnt lgkmcnt(2)
	v_pk_mul_f32 v[104:105], v[100:101], v[2:3]
	v_add_f32_e32 v106, v106, v107
	ds_read_b128 v[18:21], v98 offset:10240
	v_pk_fma_f32 v[104:105], v[102:103], v[4:5], v[104:105]
	v_add_f32_dpp v106, v106, v106 quad_perm:[1,0,3,2] row_mask:0xf bank_mask:0xf bound_ctrl:1
	v_add_f32_e32 v104, v104, v105
	s_nop 0
	v_add_f32_dpp v106, v106, v106 quad_perm:[2,3,0,1] row_mask:0xf bank_mask:0xf bound_ctrl:1
	ds_write_b32 v97, v106 offset:1280
	ds_read_b32 v40, v99 offset:12032
	ds_read_b128 v[36:39], v98 offset:11520
	v_add_f32_dpp v104, v104, v104 quad_perm:[1,0,3,2] row_mask:0xf bank_mask:0xf bound_ctrl:1
	ds_read_b128 v[24:27], v98 offset:10752
	ds_read_b128 v[28:31], v98 offset:11008
	v_add_f32_dpp v104, v104, v104 quad_perm:[2,3,0,1] row_mask:0xf bank_mask:0xf bound_ctrl:1
	v_pk_mul_f32 v[14:15], v[14:15], v[22:23] op_sel_hi:[1,0]
	v_pk_mul_f32 v[16:17], v[16:17], v[22:23] op_sel_hi:[1,0]
	v_add_f32_dpp v104, v104, v104 row_half_mirror row_mask:0xf bank_mask:0xf bound_ctrl:1
	s_waitcnt lgkmcnt(5)
	v_pk_fma_f32 v[14:15], v[100:101], v[6:7], v[14:15]
	v_pk_fma_f32 v[16:17], v[102:103], v[8:9], v[16:17]
	v_add_f32_dpp v104, v104, v104 row_mirror row_mask:0xf bank_mask:0xf bound_ctrl:1
	v_pk_fma_f32 v[100:101], v[10:11], v[104:105], v[14:15] op_sel_hi:[1,0,1] neg_lo:[0,1,0] neg_hi:[0,1,0]
	v_pk_fma_f32 v[102:103], v[12:13], v[104:105], v[16:17] op_sel_hi:[1,0,1] neg_lo:[0,1,0] neg_hi:[0,1,0]
	v_pk_mul_f32 v[106:107], v[100:101], v[18:19]
	ds_read_b128 v[32:35], v98 offset:11264
	v_pk_fma_f32 v[106:107], v[102:103], v[20:21], v[106:107]
	s_waitcnt lgkmcnt(2)
; DEVI void rwkv_scan_item(const Params& p, const int item, char* smem) {
;     ...
;   for (int c = 0; c < NC; ++c) {
;     if (wid >= 4) {
;       if (c + 1 < NC) load_chunk(c + 1, (c + 1) & 1);
;       if (c >= 1) store_y(c - 1);
;     } else {
;       const float* sb = buf + (c & 1) * 12288 + kp * 4;
;       float* yb = ybuf + (c & 1) * 2048 + row16 * 4 + (kp >> 2);
;       const int vofs = 320 + rq * 16 + row16 - kp * 4;
;       f32x4 kkA, wA, kaA, kA, rA, kkB, wB, kaB, kB, rB; float vA, vB;
;       RW_LD(0, A)
; #pragma unroll 2
;       for (int s = 0; s < 32; s += 2) {
;         RW_LD(s + 1, B)
;         __builtin_amdgcn_sched_barrier(0);
;         RW_STEP(s, A)
;         __builtin_amdgcn_sched_barrier(0);
;         if (s + 2 < 32) RW_LD(s + 2, A)
;         __builtin_amdgcn_sched_barrier(0);
;         RW_STEP(s + 1, B)
;         __builtin_amdgcn_sched_barrier(0);
;       }
	v_pk_mul_f32 v[104:105], v[100:101], v[24:25]
	v_add_f32_e32 v106, v106, v107
	ds_read_b128 v[84:87], v98 offset:11776
	v_pk_fma_f32 v[104:105], v[102:103], v[26:27], v[104:105]
	v_add_f32_dpp v106, v106, v106 quad_perm:[1,0,3,2] row_mask:0xf bank_mask:0xf bound_ctrl:1
	v_add_f32_e32 v104, v104, v105
	s_nop 0
	v_add_f32_dpp v106, v106, v106 quad_perm:[2,3,0,1] row_mask:0xf bank_mask:0xf bound_ctrl:1
	ds_write_b32 v97, v106 offset:1536
	ds_read_b32 v22, v99 offset:13568
	ds_read_b128 v[14:17], v98 offset:13056
	v_add_f32_dpp v104, v104, v104 quad_perm:[1,0,3,2] row_mask:0xf bank_mask:0xf bound_ctrl:1
	ds_read_b128 v[2:5], v98 offset:12288
	ds_read_b128 v[6:9], v98 offset:12544
	v_add_f32_dpp v104, v104, v104 quad_perm:[2,3,0,1] row_mask:0xf bank_mask:0xf bound_ctrl:1
	v_pk_mul_f32 v[36:37], v[36:37], v[40:41] op_sel_hi:[1,0]
	v_pk_mul_f32 v[38:39], v[38:39], v[40:41] op_sel_hi:[1,0]
	v_add_f32_dpp v104, v104, v104 row_half_mirror row_mask:0xf bank_mask:0xf bound_ctrl:1
	s_waitcnt lgkmcnt(5)
	v_pk_fma_f32 v[36:37], v[100:101], v[28:29], v[36:37]
	v_pk_fma_f32 v[38:39], v[102:103], v[30:31], v[38:39]
	v_add_f32_dpp v104, v104, v104 row_mirror row_mask:0xf bank_mask:0xf bound_ctrl:1
	v_pk_fma_f32 v[100:101], v[32:33], v[104:105], v[36:37] op_sel_hi:[1,0,1] neg_lo:[0,1,0] neg_hi:[0,1,0]
	v_pk_fma_f32 v[102:103], v[34:35], v[104:105], v[38:39] op_sel_hi:[1,0,1] neg_lo:[0,1,0] neg_hi:[0,1,0]
	v_pk_mul_f32 v[106:107], v[100:101], v[84:85]
	ds_read_b128 v[10:13], v98 offset:12800
	v_pk_fma_f32 v[106:107], v[102:103], v[86:87], v[106:107]
	s_waitcnt lgkmcnt(2)
	v_pk_mul_f32 v[104:105], v[100:101], v[2:3]
	v_add_f32_e32 v106, v106, v107
	ds_read_b128 v[18:21], v98 offset:13312
	v_pk_fma_f32 v[104:105], v[102:103], v[4:5], v[104:105]
	v_add_f32_dpp v106, v106, v106 quad_perm:[1,0,3,2] row_mask:0xf bank_mask:0xf bound_ctrl:1
	v_add_f32_e32 v104, v104, v105
	s_nop 0
	v_add_f32_dpp v106, v106, v106 quad_perm:[2,3,0,1] row_mask:0xf bank_mask:0xf bound_ctrl:1
	ds_write_b32 v97, v106 offset:1792
	ds_read_b32 v40, v99 offset:15104
	ds_read_b128 v[36:39], v98 offset:14592
	v_add_f32_dpp v104, v104, v104 quad_perm:[1,0,3,2] row_mask:0xf bank_mask:0xf bound_ctrl:1
	ds_read_b128 v[24:27], v98 offset:13824
	ds_read_b128 v[28:31], v98 offset:14080
	v_add_f32_dpp v104, v104, v104 quad_perm:[2,3,0,1] row_mask:0xf bank_mask:0xf bound_ctrl:1
	v_pk_mul_f32 v[14:15], v[14:15], v[22:23] op_sel_hi:[1,0]
	v_pk_mul_f32 v[16:17], v[16:17], v[22:23] op_sel_hi:[1,0]
	v_add_f32_dpp v104, v104, v104 row_half_mirror row_mask:0xf bank_mask:0xf bound_ctrl:1
	s_waitcnt lgkmcnt(5)
	v_pk_fma_f32 v[14:15], v[100:101], v[6:7], v[14:15]
	v_pk_fma_f32 v[16:17], v[102:103], v[8:9], v[16:17]
	v_add_f32_dpp v104, v104, v104 row_mirror row_mask:0xf bank_mask:0xf bound_ctrl:1
	v_pk_fma_f32 v[100:101], v[10:11], v[104:105], v[14:15] op_sel_hi:[1,0,1] neg_lo:[0,1,0] neg_hi:[0,1,0]
	v_pk_fma_f32 v[102:103], v[12:13], v[104:105], v[16:17] op_sel_hi:[1,0,1] neg_lo:[0,1,0] neg_hi:[0,1,0]
	v_pk_mul_f32 v[106:107], v[100:101], v[18:19]
	ds_read_b128 v[32:35], v98 offset:14336
	v_pk_fma_f32 v[106:107], v[102:103], v[20:21], v[106:107]
	s_waitcnt lgkmcnt(2)
	v_pk_mul_f32 v[104:105], v[100:101], v[24:25]
	v_add_f32_e32 v106, v106, v107
	ds_read_b128 v[84:87], v98 offset:14848
	v_pk_fma_f32 v[104:105], v[102:103], v[26:27], v[104:105]
	v_add_f32_dpp v106, v106, v106 quad_perm:[1,0,3,2] row_mask:0xf bank_mask:0xf bound_ctrl:1
	v_add_f32_e32 v104, v104, v105
	s_nop 0
	v_add_f32_dpp v106, v106, v106 quad_perm:[2,3,0,1] row_mask:0xf bank_mask:0xf bound_ctrl:1
	ds_write_b32 v97, v106 offset:2048
	ds_read_b32 v22, v99 offset:16640
	ds_read_b128 v[14:17], v98 offset:16128
	v_add_f32_dpp v104, v104, v104 quad_perm:[1,0,3,2] row_mask:0xf bank_mask:0xf bound_ctrl:1
	ds_read_b128 v[2:5], v98 offset:15360
	ds_read_b128 v[6:9], v98 offset:15616
	v_add_f32_dpp v104, v104, v104 quad_perm:[2,3,0,1] row_mask:0xf bank_mask:0xf bound_ctrl:1
	v_pk_mul_f32 v[36:37], v[36:37], v[40:41] op_sel_hi:[1,0]
	v_pk_mul_f32 v[38:39], v[38:39], v[40:41] op_sel_hi:[1,0]
	v_add_f32_dpp v104, v104, v104 row_half_mirror row_mask:0xf bank_mask:0xf bound_ctrl:1
	s_waitcnt lgkmcnt(5)
	v_pk_fma_f32 v[36:37], v[100:101], v[28:29], v[36:37]
	v_pk_fma_f32 v[38:39], v[102:103], v[30:31], v[38:39]
	v_add_f32_dpp v104, v104, v104 row_mirror row_mask:0xf bank_mask:0xf bound_ctrl:1
	v_pk_fma_f32 v[100:101], v[32:33], v[104:105], v[36:37] op_sel_hi:[1,0,1] neg_lo:[0,1,0] neg_hi:[0,1,0]
	v_pk_fma_f32 v[102:103], v[34:35], v[104:105], v[38:39] op_sel_hi:[1,0,1] neg_lo:[0,1,0] neg_hi:[0,1,0]
	v_pk_mul_f32 v[106:107], v[100:101], v[84:85]
	ds_read_b128 v[10:13], v98 offset:15872
	v_pk_fma_f32 v[106:107], v[102:103], v[86:87], v[106:107]
	s_waitcnt lgkmcnt(2)
	v_pk_mul_f32 v[104:105], v[100:101], v[2:3]
	v_add_f32_e32 v106, v106, v107
	ds_read_b128 v[18:21], v98 offset:16384
	v_pk_fma_f32 v[104:105], v[102:103], v[4:5], v[104:105]
	v_add_f32_dpp v106, v106, v106 quad_perm:[1,0,3,2] row_mask:0xf bank_mask:0xf bound_ctrl:1
	v_add_f32_e32 v104, v104, v105
	s_nop 0
	v_add_f32_dpp v106, v106, v106 quad_perm:[2,3,0,1] row_mask:0xf bank_mask:0xf bound_ctrl:1
	ds_write_b32 v97, v106 offset:2304
	ds_read_b32 v40, v99 offset:18176
	ds_read_b128 v[36:39], v98 offset:17664
	v_add_f32_dpp v104, v104, v104 quad_perm:[1,0,3,2] row_mask:0xf bank_mask:0xf bound_ctrl:1
	ds_read_b128 v[24:27], v98 offset:16896
	ds_read_b128 v[28:31], v98 offset:17152
	v_add_f32_dpp v104, v104, v104 quad_perm:[2,3,0,1] row_mask:0xf bank_mask:0xf bound_ctrl:1
	v_pk_mul_f32 v[14:15], v[14:15], v[22:23] op_sel_hi:[1,0]
	v_pk_mul_f32 v[16:17], v[16:17], v[22:23] op_sel_hi:[1,0]
	v_add_f32_dpp v104, v104, v104 row_half_mirror row_mask:0xf bank_mask:0xf bound_ctrl:1
	s_waitcnt lgkmcnt(5)
; DEVI void rwkv_scan_item(const Params& p, const int item, char* smem) {
;     ...
;   for (int c = 0; c < NC; ++c) {
;     if (wid >= 4) {
;       if (c + 1 < NC) load_chunk(c + 1, (c + 1) & 1);
;       if (c >= 1) store_y(c - 1);
;     } else {
;       const float* sb = buf + (c & 1) * 12288 + kp * 4;
;       float* yb = ybuf + (c & 1) * 2048 + row16 * 4 + (kp >> 2);
;       const int vofs = 320 + rq * 16 + row16 - kp * 4;
;       f32x4 kkA, wA, kaA, kA, rA, kkB, wB, kaB, kB, rB; float vA, vB;
;       RW_LD(0, A)
; #pragma unroll 2
;       for (int s = 0; s < 32; s += 2) {
;         RW_LD(s + 1, B)
;         __builtin_amdgcn_sched_barrier(0);
;         RW_STEP(s, A)
;         __builtin_amdgcn_sched_barrier(0);
;         if (s + 2 < 32) RW_LD(s + 2, A)
;         __builtin_amdgcn_sched_barrier(0);
;         RW_STEP(s + 1, B)
;         __builtin_amdgcn_sched_barrier(0);
;       }
	v_pk_fma_f32 v[14:15], v[100:101], v[6:7], v[14:15]
	v_pk_fma_f32 v[16:17], v[102:103], v[8:9], v[16:17]
	v_add_f32_dpp v104, v104, v104 row_mirror row_mask:0xf bank_mask:0xf bound_ctrl:1
	v_pk_fma_f32 v[100:101], v[10:11], v[104:105], v[14:15] op_sel_hi:[1,0,1] neg_lo:[0,1,0] neg_hi:[0,1,0]
	v_pk_fma_f32 v[102:103], v[12:13], v[104:105], v[16:17] op_sel_hi:[1,0,1] neg_lo:[0,1,0] neg_hi:[0,1,0]
	v_pk_mul_f32 v[106:107], v[100:101], v[18:19]
	ds_read_b128 v[32:35], v98 offset:17408
	v_pk_fma_f32 v[106:107], v[102:103], v[20:21], v[106:107]
	s_waitcnt lgkmcnt(2)
	v_pk_mul_f32 v[104:105], v[100:101], v[24:25]
	v_add_f32_e32 v106, v106, v107
	ds_read_b128 v[84:87], v98 offset:17920
	v_pk_fma_f32 v[104:105], v[102:103], v[26:27], v[104:105]
	v_add_f32_dpp v106, v106, v106 quad_perm:[1,0,3,2] row_mask:0xf bank_mask:0xf bound_ctrl:1
	v_add_f32_e32 v104, v104, v105
	s_nop 0
	v_add_f32_dpp v106, v106, v106 quad_perm:[2,3,0,1] row_mask:0xf bank_mask:0xf bound_ctrl:1
	ds_write_b32 v97, v106 offset:2560
	ds_read_b32 v22, v99 offset:19712
	ds_read_b128 v[14:17], v98 offset:19200
	v_add_f32_dpp v104, v104, v104 quad_perm:[1,0,3,2] row_mask:0xf bank_mask:0xf bound_ctrl:1
	ds_read_b128 v[2:5], v98 offset:18432
	ds_read_b128 v[6:9], v98 offset:18688
	v_add_f32_dpp v104, v104, v104 quad_perm:[2,3,0,1] row_mask:0xf bank_mask:0xf bound_ctrl:1
	v_pk_mul_f32 v[36:37], v[36:37], v[40:41] op_sel_hi:[1,0]
	v_pk_mul_f32 v[38:39], v[38:39], v[40:41] op_sel_hi:[1,0]
	v_add_f32_dpp v104, v104, v104 row_half_mirror row_mask:0xf bank_mask:0xf bound_ctrl:1
	s_waitcnt lgkmcnt(5)
	v_pk_fma_f32 v[36:37], v[100:101], v[28:29], v[36:37]
	v_pk_fma_f32 v[38:39], v[102:103], v[30:31], v[38:39]
	v_add_f32_dpp v104, v104, v104 row_mirror row_mask:0xf bank_mask:0xf bound_ctrl:1
	v_pk_fma_f32 v[100:101], v[32:33], v[104:105], v[36:37] op_sel_hi:[1,0,1] neg_lo:[0,1,0] neg_hi:[0,1,0]
	v_pk_fma_f32 v[102:103], v[34:35], v[104:105], v[38:39] op_sel_hi:[1,0,1] neg_lo:[0,1,0] neg_hi:[0,1,0]
	v_pk_mul_f32 v[106:107], v[100:101], v[84:85]
	ds_read_b128 v[10:13], v98 offset:18944
	v_pk_fma_f32 v[106:107], v[102:103], v[86:87], v[106:107]
	s_waitcnt lgkmcnt(2)
	v_pk_mul_f32 v[104:105], v[100:101], v[2:3]
	v_add_f32_e32 v106, v106, v107
	ds_read_b128 v[18:21], v98 offset:19456
	v_pk_fma_f32 v[104:105], v[102:103], v[4:5], v[104:105]
	v_add_f32_dpp v106, v106, v106 quad_perm:[1,0,3,2] row_mask:0xf bank_mask:0xf bound_ctrl:1
	v_add_f32_e32 v104, v104, v105
	s_nop 0
	v_add_f32_dpp v106, v106, v106 quad_perm:[2,3,0,1] row_mask:0xf bank_mask:0xf bound_ctrl:1
	ds_write_b32 v97, v106 offset:2816
	ds_read_b32 v40, v99 offset:21248
	ds_read_b128 v[36:39], v98 offset:20736
	v_add_f32_dpp v104, v104, v104 quad_perm:[1,0,3,2] row_mask:0xf bank_mask:0xf bound_ctrl:1
	ds_read_b128 v[24:27], v98 offset:19968
	ds_read_b128 v[28:31], v98 offset:20224
	v_add_f32_dpp v104, v104, v104 quad_perm:[2,3,0,1] row_mask:0xf bank_mask:0xf bound_ctrl:1
	v_pk_mul_f32 v[14:15], v[14:15], v[22:23] op_sel_hi:[1,0]
	v_pk_mul_f32 v[16:17], v[16:17], v[22:23] op_sel_hi:[1,0]
	v_add_f32_dpp v104, v104, v104 row_half_mirror row_mask:0xf bank_mask:0xf bound_ctrl:1
	s_waitcnt lgkmcnt(5)
	v_pk_fma_f32 v[14:15], v[100:101], v[6:7], v[14:15]
	v_pk_fma_f32 v[16:17], v[102:103], v[8:9], v[16:17]
	v_add_f32_dpp v104, v104, v104 row_mirror row_mask:0xf bank_mask:0xf bound_ctrl:1
	v_pk_fma_f32 v[100:101], v[10:11], v[104:105], v[14:15] op_sel_hi:[1,0,1] neg_lo:[0,1,0] neg_hi:[0,1,0]
	v_pk_fma_f32 v[102:103], v[12:13], v[104:105], v[16:17] op_sel_hi:[1,0,1] neg_lo:[0,1,0] neg_hi:[0,1,0]
	v_pk_mul_f32 v[106:107], v[100:101], v[18:19]
	ds_read_b128 v[32:35], v98 offset:20480
	v_pk_fma_f32 v[106:107], v[102:103], v[20:21], v[106:107]
	s_waitcnt lgkmcnt(2)
	v_pk_mul_f32 v[104:105], v[100:101], v[24:25]
	v_add_f32_e32 v106, v106, v107
	ds_read_b128 v[84:87], v98 offset:20992
	v_pk_fma_f32 v[104:105], v[102:103], v[26:27], v[104:105]
	v_add_f32_dpp v106, v106, v106 quad_perm:[1,0,3,2] row_mask:0xf bank_mask:0xf bound_ctrl:1
	v_add_f32_e32 v104, v104, v105
	s_nop 0
	v_add_f32_dpp v106, v106, v106 quad_perm:[2,3,0,1] row_mask:0xf bank_mask:0xf bound_ctrl:1
	ds_write_b32 v97, v106 offset:3072
	ds_read_b32 v22, v99 offset:22784
	ds_read_b128 v[14:17], v98 offset:22272
	v_add_f32_dpp v104, v104, v104 quad_perm:[1,0,3,2] row_mask:0xf bank_mask:0xf bound_ctrl:1
	ds_read_b128 v[2:5], v98 offset:21504
	ds_read_b128 v[6:9], v98 offset:21760
	v_add_f32_dpp v104, v104, v104 quad_perm:[2,3,0,1] row_mask:0xf bank_mask:0xf bound_ctrl:1
	v_pk_mul_f32 v[36:37], v[36:37], v[40:41] op_sel_hi:[1,0]
	v_pk_mul_f32 v[38:39], v[38:39], v[40:41] op_sel_hi:[1,0]
	v_add_f32_dpp v104, v104, v104 row_half_mirror row_mask:0xf bank_mask:0xf bound_ctrl:1
	s_waitcnt lgkmcnt(5)
	v_pk_fma_f32 v[36:37], v[100:101], v[28:29], v[36:37]
	v_pk_fma_f32 v[38:39], v[102:103], v[30:31], v[38:39]
	v_add_f32_dpp v104, v104, v104 row_mirror row_mask:0xf bank_mask:0xf bound_ctrl:1
	v_pk_fma_f32 v[100:101], v[32:33], v[104:105], v[36:37] op_sel_hi:[1,0,1] neg_lo:[0,1,0] neg_hi:[0,1,0]
	v_pk_fma_f32 v[102:103], v[34:35], v[104:105], v[38:39] op_sel_hi:[1,0,1] neg_lo:[0,1,0] neg_hi:[0,1,0]
	v_pk_mul_f32 v[106:107], v[100:101], v[84:85]
	ds_read_b128 v[10:13], v98 offset:22016
	v_pk_fma_f32 v[106:107], v[102:103], v[86:87], v[106:107]
	s_waitcnt lgkmcnt(2)
; DEVI void rwkv_scan_item(const Params& p, const int item, char* smem) {
;     ...
;   for (int c = 0; c < NC; ++c) {
;     if (wid >= 4) {
;       if (c + 1 < NC) load_chunk(c + 1, (c + 1) & 1);
;       if (c >= 1) store_y(c - 1);
;     } else {
;       const float* sb = buf + (c & 1) * 12288 + kp * 4;
;       float* yb = ybuf + (c & 1) * 2048 + row16 * 4 + (kp >> 2);
;       const int vofs = 320 + rq * 16 + row16 - kp * 4;
;       f32x4 kkA, wA, kaA, kA, rA, kkB, wB, kaB, kB, rB; float vA, vB;
;       RW_LD(0, A)
; #pragma unroll 2
;       for (int s = 0; s < 32; s += 2) {
;         RW_LD(s + 1, B)
;         __builtin_amdgcn_sched_barrier(0);
;         RW_STEP(s, A)
;         __builtin_amdgcn_sched_barrier(0);
;         if (s + 2 < 32) RW_LD(s + 2, A)
;         __builtin_amdgcn_sched_barrier(0);
;         RW_STEP(s + 1, B)
;         __builtin_amdgcn_sched_barrier(0);
;       }
	v_pk_mul_f32 v[104:105], v[100:101], v[2:3]
	v_add_f32_e32 v106, v106, v107
	ds_read_b128 v[18:21], v98 offset:22528
	v_pk_fma_f32 v[104:105], v[102:103], v[4:5], v[104:105]
	v_add_f32_dpp v106, v106, v106 quad_perm:[1,0,3,2] row_mask:0xf bank_mask:0xf bound_ctrl:1
	v_add_f32_e32 v104, v104, v105
	s_nop 0
	v_add_f32_dpp v106, v106, v106 quad_perm:[2,3,0,1] row_mask:0xf bank_mask:0xf bound_ctrl:1
	ds_write_b32 v97, v106 offset:3328
	ds_read_b32 v40, v99 offset:24320
	ds_read_b128 v[36:39], v98 offset:23808
	v_add_f32_dpp v104, v104, v104 quad_perm:[1,0,3,2] row_mask:0xf bank_mask:0xf bound_ctrl:1
	ds_read_b128 v[24:27], v98 offset:23040
	ds_read_b128 v[28:31], v98 offset:23296
	v_add_f32_dpp v104, v104, v104 quad_perm:[2,3,0,1] row_mask:0xf bank_mask:0xf bound_ctrl:1
	v_pk_mul_f32 v[14:15], v[14:15], v[22:23] op_sel_hi:[1,0]
	v_pk_mul_f32 v[16:17], v[16:17], v[22:23] op_sel_hi:[1,0]
	v_add_f32_dpp v104, v104, v104 row_half_mirror row_mask:0xf bank_mask:0xf bound_ctrl:1
	s_waitcnt lgkmcnt(5)
	v_pk_fma_f32 v[14:15], v[100:101], v[6:7], v[14:15]
	v_pk_fma_f32 v[16:17], v[102:103], v[8:9], v[16:17]
	v_add_f32_dpp v104, v104, v104 row_mirror row_mask:0xf bank_mask:0xf bound_ctrl:1
	v_pk_fma_f32 v[100:101], v[10:11], v[104:105], v[14:15] op_sel_hi:[1,0,1] neg_lo:[0,1,0] neg_hi:[0,1,0]
	v_pk_fma_f32 v[102:103], v[12:13], v[104:105], v[16:17] op_sel_hi:[1,0,1] neg_lo:[0,1,0] neg_hi:[0,1,0]
	v_pk_mul_f32 v[106:107], v[100:101], v[18:19]
	ds_read_b128 v[32:35], v98 offset:23552
	v_pk_fma_f32 v[106:107], v[102:103], v[20:21], v[106:107]
	s_waitcnt lgkmcnt(2)
	v_pk_mul_f32 v[104:105], v[100:101], v[24:25]
	v_add_f32_e32 v106, v106, v107
	ds_read_b128 v[84:87], v98 offset:24064
	v_pk_fma_f32 v[104:105], v[102:103], v[26:27], v[104:105]
	v_add_f32_dpp v106, v106, v106 quad_perm:[1,0,3,2] row_mask:0xf bank_mask:0xf bound_ctrl:1
	v_add_f32_e32 v104, v104, v105
	s_nop 0
	v_add_f32_dpp v106, v106, v106 quad_perm:[2,3,0,1] row_mask:0xf bank_mask:0xf bound_ctrl:1
	ds_write_b32 v97, v106 offset:3584
	ds_read_b32 v22, v99 offset:25856
	ds_read_b128 v[14:17], v98 offset:25344
	v_add_f32_dpp v104, v104, v104 quad_perm:[1,0,3,2] row_mask:0xf bank_mask:0xf bound_ctrl:1
	ds_read_b128 v[2:5], v98 offset:24576
	ds_read_b128 v[6:9], v98 offset:24832
	v_add_f32_dpp v104, v104, v104 quad_perm:[2,3,0,1] row_mask:0xf bank_mask:0xf bound_ctrl:1
	v_pk_mul_f32 v[36:37], v[36:37], v[40:41] op_sel_hi:[1,0]
	v_pk_mul_f32 v[38:39], v[38:39], v[40:41] op_sel_hi:[1,0]
	v_add_f32_dpp v104, v104, v104 row_half_mirror row_mask:0xf bank_mask:0xf bound_ctrl:1
	s_waitcnt lgkmcnt(5)
	v_pk_fma_f32 v[36:37], v[100:101], v[28:29], v[36:37]
	v_pk_fma_f32 v[38:39], v[102:103], v[30:31], v[38:39]
	v_add_f32_dpp v104, v104, v104 row_mirror row_mask:0xf bank_mask:0xf bound_ctrl:1
	v_pk_fma_f32 v[100:101], v[32:33], v[104:105], v[36:37] op_sel_hi:[1,0,1] neg_lo:[0,1,0] neg_hi:[0,1,0]
	v_pk_fma_f32 v[102:103], v[34:35], v[104:105], v[38:39] op_sel_hi:[1,0,1] neg_lo:[0,1,0] neg_hi:[0,1,0]
	v_pk_mul_f32 v[106:107], v[100:101], v[84:85]
	ds_read_b128 v[10:13], v98 offset:25088
	v_pk_fma_f32 v[106:107], v[102:103], v[86:87], v[106:107]
	s_waitcnt lgkmcnt(2)
	v_pk_mul_f32 v[104:105], v[100:101], v[2:3]
	v_add_f32_e32 v106, v106, v107
	ds_read_b128 v[18:21], v98 offset:25600
	v_pk_fma_f32 v[104:105], v[102:103], v[4:5], v[104:105]
	v_add_f32_dpp v106, v106, v106 quad_perm:[1,0,3,2] row_mask:0xf bank_mask:0xf bound_ctrl:1
	v_add_f32_e32 v104, v104, v105
	s_nop 0
	v_add_f32_dpp v106, v106, v106 quad_perm:[2,3,0,1] row_mask:0xf bank_mask:0xf bound_ctrl:1
	ds_write_b32 v97, v106 offset:3840
	ds_read_b32 v40, v99 offset:27392
	ds_read_b128 v[36:39], v98 offset:26880
	v_add_f32_dpp v104, v104, v104 quad_perm:[1,0,3,2] row_mask:0xf bank_mask:0xf bound_ctrl:1
	ds_read_b128 v[24:27], v98 offset:26112
	ds_read_b128 v[28:31], v98 offset:26368
	v_add_f32_dpp v104, v104, v104 quad_perm:[2,3,0,1] row_mask:0xf bank_mask:0xf bound_ctrl:1
	v_pk_mul_f32 v[14:15], v[14:15], v[22:23] op_sel_hi:[1,0]
	v_pk_mul_f32 v[16:17], v[16:17], v[22:23] op_sel_hi:[1,0]
	v_add_f32_dpp v104, v104, v104 row_half_mirror row_mask:0xf bank_mask:0xf bound_ctrl:1
	s_waitcnt lgkmcnt(5)
	v_pk_fma_f32 v[14:15], v[100:101], v[6:7], v[14:15]
	v_pk_fma_f32 v[16:17], v[102:103], v[8:9], v[16:17]
	v_add_f32_dpp v104, v104, v104 row_mirror row_mask:0xf bank_mask:0xf bound_ctrl:1
	v_pk_fma_f32 v[100:101], v[10:11], v[104:105], v[14:15] op_sel_hi:[1,0,1] neg_lo:[0,1,0] neg_hi:[0,1,0]
	v_pk_fma_f32 v[102:103], v[12:13], v[104:105], v[16:17] op_sel_hi:[1,0,1] neg_lo:[0,1,0] neg_hi:[0,1,0]
	v_pk_mul_f32 v[106:107], v[100:101], v[18:19]
	ds_read_b128 v[32:35], v98 offset:26624
	v_pk_fma_f32 v[106:107], v[102:103], v[20:21], v[106:107]
	s_waitcnt lgkmcnt(2)
	v_pk_mul_f32 v[104:105], v[100:101], v[24:25]
	v_add_f32_e32 v106, v106, v107
	ds_read_b128 v[84:87], v98 offset:27136
	v_pk_fma_f32 v[104:105], v[102:103], v[26:27], v[104:105]
	v_add_f32_dpp v106, v106, v106 quad_perm:[1,0,3,2] row_mask:0xf bank_mask:0xf bound_ctrl:1
	v_add_f32_e32 v104, v104, v105
	s_nop 0
	v_add_f32_dpp v106, v106, v106 quad_perm:[2,3,0,1] row_mask:0xf bank_mask:0xf bound_ctrl:1
	ds_write_b32 v97, v106 offset:4096
	ds_read_b32 v22, v99 offset:28928
	ds_read_b128 v[14:17], v98 offset:28416
	v_add_f32_dpp v104, v104, v104 quad_perm:[1,0,3,2] row_mask:0xf bank_mask:0xf bound_ctrl:1
	ds_read_b128 v[2:5], v98 offset:27648
	ds_read_b128 v[6:9], v98 offset:27904
	v_add_f32_dpp v104, v104, v104 quad_perm:[2,3,0,1] row_mask:0xf bank_mask:0xf bound_ctrl:1
	v_pk_mul_f32 v[36:37], v[36:37], v[40:41] op_sel_hi:[1,0]
	v_pk_mul_f32 v[38:39], v[38:39], v[40:41] op_sel_hi:[1,0]
	v_add_f32_dpp v104, v104, v104 row_half_mirror row_mask:0xf bank_mask:0xf bound_ctrl:1
	s_waitcnt lgkmcnt(5)
; DEVI void rwkv_scan_item(const Params& p, const int item, char* smem) {
;     ...
;   for (int c = 0; c < NC; ++c) {
;     if (wid >= 4) {
;       if (c + 1 < NC) load_chunk(c + 1, (c + 1) & 1);
;       if (c >= 1) store_y(c - 1);
;     } else {
;       const float* sb = buf + (c & 1) * 12288 + kp * 4;
;       float* yb = ybuf + (c & 1) * 2048 + row16 * 4 + (kp >> 2);
;       const int vofs = 320 + rq * 16 + row16 - kp * 4;
;       f32x4 kkA, wA, kaA, kA, rA, kkB, wB, kaB, kB, rB; float vA, vB;
;       RW_LD(0, A)
; #pragma unroll 2
;       for (int s = 0; s < 32; s += 2) {
;         RW_LD(s + 1, B)
;         __builtin_amdgcn_sched_barrier(0);
;         RW_STEP(s, A)
;         __builtin_amdgcn_sched_barrier(0);
;         if (s + 2 < 32) RW_LD(s + 2, A)
;         __builtin_amdgcn_sched_barrier(0);
;         RW_STEP(s + 1, B)
;         __builtin_amdgcn_sched_barrier(0);
;       }
	v_pk_fma_f32 v[36:37], v[100:101], v[28:29], v[36:37]
	v_pk_fma_f32 v[38:39], v[102:103], v[30:31], v[38:39]
	v_add_f32_dpp v104, v104, v104 row_mirror row_mask:0xf bank_mask:0xf bound_ctrl:1
	v_pk_fma_f32 v[100:101], v[32:33], v[104:105], v[36:37] op_sel_hi:[1,0,1] neg_lo:[0,1,0] neg_hi:[0,1,0]
	v_pk_fma_f32 v[102:103], v[34:35], v[104:105], v[38:39] op_sel_hi:[1,0,1] neg_lo:[0,1,0] neg_hi:[0,1,0]
	v_pk_mul_f32 v[106:107], v[100:101], v[84:85]
	ds_read_b128 v[10:13], v98 offset:28160
	v_pk_fma_f32 v[106:107], v[102:103], v[86:87], v[106:107]
	s_waitcnt lgkmcnt(2)
	v_pk_mul_f32 v[104:105], v[100:101], v[2:3]
	v_add_f32_e32 v106, v106, v107
	ds_read_b128 v[18:21], v98 offset:28672
	v_pk_fma_f32 v[104:105], v[102:103], v[4:5], v[104:105]
	v_add_f32_dpp v106, v106, v106 quad_perm:[1,0,3,2] row_mask:0xf bank_mask:0xf bound_ctrl:1
	v_add_f32_e32 v104, v104, v105
	s_nop 0
	v_add_f32_dpp v106, v106, v106 quad_perm:[2,3,0,1] row_mask:0xf bank_mask:0xf bound_ctrl:1
	ds_write_b32 v97, v106 offset:4352
	ds_read_b32 v40, v99 offset:30464
	ds_read_b128 v[36:39], v98 offset:29952
	v_add_f32_dpp v104, v104, v104 quad_perm:[1,0,3,2] row_mask:0xf bank_mask:0xf bound_ctrl:1
	ds_read_b128 v[24:27], v98 offset:29184
	ds_read_b128 v[28:31], v98 offset:29440
	v_add_f32_dpp v104, v104, v104 quad_perm:[2,3,0,1] row_mask:0xf bank_mask:0xf bound_ctrl:1
	v_pk_mul_f32 v[14:15], v[14:15], v[22:23] op_sel_hi:[1,0]
	v_pk_mul_f32 v[16:17], v[16:17], v[22:23] op_sel_hi:[1,0]
	v_add_f32_dpp v104, v104, v104 row_half_mirror row_mask:0xf bank_mask:0xf bound_ctrl:1
	s_waitcnt lgkmcnt(5)
	v_pk_fma_f32 v[14:15], v[100:101], v[6:7], v[14:15]
	v_pk_fma_f32 v[16:17], v[102:103], v[8:9], v[16:17]
	v_add_f32_dpp v104, v104, v104 row_mirror row_mask:0xf bank_mask:0xf bound_ctrl:1
	v_pk_fma_f32 v[100:101], v[10:11], v[104:105], v[14:15] op_sel_hi:[1,0,1] neg_lo:[0,1,0] neg_hi:[0,1,0]
	v_pk_fma_f32 v[102:103], v[12:13], v[104:105], v[16:17] op_sel_hi:[1,0,1] neg_lo:[0,1,0] neg_hi:[0,1,0]
	v_pk_mul_f32 v[106:107], v[100:101], v[18:19]
	ds_read_b128 v[32:35], v98 offset:29696
	v_pk_fma_f32 v[106:107], v[102:103], v[20:21], v[106:107]
	s_waitcnt lgkmcnt(2)
	v_pk_mul_f32 v[104:105], v[100:101], v[24:25]
	v_add_f32_e32 v106, v106, v107
	ds_read_b128 v[84:87], v98 offset:30208
	v_pk_fma_f32 v[104:105], v[102:103], v[26:27], v[104:105]
	v_add_f32_dpp v106, v106, v106 quad_perm:[1,0,3,2] row_mask:0xf bank_mask:0xf bound_ctrl:1
	v_add_f32_e32 v104, v104, v105
	s_nop 0
	v_add_f32_dpp v106, v106, v106 quad_perm:[2,3,0,1] row_mask:0xf bank_mask:0xf bound_ctrl:1
	ds_write_b32 v97, v106 offset:4608
	ds_read_b32 v22, v99 offset:32000
	ds_read_b128 v[14:17], v98 offset:31488
	v_add_f32_dpp v104, v104, v104 quad_perm:[1,0,3,2] row_mask:0xf bank_mask:0xf bound_ctrl:1
	ds_read_b128 v[2:5], v98 offset:30720
	ds_read_b128 v[6:9], v98 offset:30976
	v_add_f32_dpp v104, v104, v104 quad_perm:[2,3,0,1] row_mask:0xf bank_mask:0xf bound_ctrl:1
	v_pk_mul_f32 v[36:37], v[36:37], v[40:41] op_sel_hi:[1,0]
	v_pk_mul_f32 v[38:39], v[38:39], v[40:41] op_sel_hi:[1,0]
	v_add_f32_dpp v104, v104, v104 row_half_mirror row_mask:0xf bank_mask:0xf bound_ctrl:1
	s_waitcnt lgkmcnt(5)
	v_pk_fma_f32 v[36:37], v[100:101], v[28:29], v[36:37]
	v_pk_fma_f32 v[38:39], v[102:103], v[30:31], v[38:39]
	v_add_f32_dpp v104, v104, v104 row_mirror row_mask:0xf bank_mask:0xf bound_ctrl:1
	v_pk_fma_f32 v[100:101], v[32:33], v[104:105], v[36:37] op_sel_hi:[1,0,1] neg_lo:[0,1,0] neg_hi:[0,1,0]
	v_pk_fma_f32 v[102:103], v[34:35], v[104:105], v[38:39] op_sel_hi:[1,0,1] neg_lo:[0,1,0] neg_hi:[0,1,0]
	v_pk_mul_f32 v[106:107], v[100:101], v[84:85]
	ds_read_b128 v[10:13], v98 offset:31232
	v_pk_fma_f32 v[106:107], v[102:103], v[86:87], v[106:107]
	s_waitcnt lgkmcnt(2)
	v_pk_mul_f32 v[104:105], v[100:101], v[2:3]
	v_add_f32_e32 v106, v106, v107
	ds_read_b128 v[18:21], v98 offset:31744
	v_pk_fma_f32 v[104:105], v[102:103], v[4:5], v[104:105]
	v_add_f32_dpp v106, v106, v106 quad_perm:[1,0,3,2] row_mask:0xf bank_mask:0xf bound_ctrl:1
	v_add_f32_e32 v104, v104, v105
	s_nop 0
	v_add_f32_dpp v106, v106, v106 quad_perm:[2,3,0,1] row_mask:0xf bank_mask:0xf bound_ctrl:1
	ds_write_b32 v97, v106 offset:4864
	ds_read_b32 v40, v99 offset:33536
	ds_read_b128 v[36:39], v98 offset:33024
	v_add_f32_dpp v104, v104, v104 quad_perm:[1,0,3,2] row_mask:0xf bank_mask:0xf bound_ctrl:1
	ds_read_b128 v[24:27], v98 offset:32256
	ds_read_b128 v[28:31], v98 offset:32512
	v_add_f32_dpp v104, v104, v104 quad_perm:[2,3,0,1] row_mask:0xf bank_mask:0xf bound_ctrl:1
	v_pk_mul_f32 v[14:15], v[14:15], v[22:23] op_sel_hi:[1,0]
	v_pk_mul_f32 v[16:17], v[16:17], v[22:23] op_sel_hi:[1,0]
	v_add_f32_dpp v104, v104, v104 row_half_mirror row_mask:0xf bank_mask:0xf bound_ctrl:1
	s_waitcnt lgkmcnt(5)
	v_pk_fma_f32 v[14:15], v[100:101], v[6:7], v[14:15]
	v_pk_fma_f32 v[16:17], v[102:103], v[8:9], v[16:17]
	v_add_f32_dpp v104, v104, v104 row_mirror row_mask:0xf bank_mask:0xf bound_ctrl:1
	v_pk_fma_f32 v[100:101], v[10:11], v[104:105], v[14:15] op_sel_hi:[1,0,1] neg_lo:[0,1,0] neg_hi:[0,1,0]
	v_pk_fma_f32 v[102:103], v[12:13], v[104:105], v[16:17] op_sel_hi:[1,0,1] neg_lo:[0,1,0] neg_hi:[0,1,0]
	v_pk_mul_f32 v[106:107], v[100:101], v[18:19]
	ds_read_b128 v[32:35], v98 offset:32768
	v_pk_fma_f32 v[106:107], v[102:103], v[20:21], v[106:107]
	s_waitcnt lgkmcnt(2)
; DEVI void rwkv_scan_item(const Params& p, const int item, char* smem) {
;     ...
;   for (int c = 0; c < NC; ++c) {
;     if (wid >= 4) {
;       if (c + 1 < NC) load_chunk(c + 1, (c + 1) & 1);
;       if (c >= 1) store_y(c - 1);
;     } else {
;       const float* sb = buf + (c & 1) * 12288 + kp * 4;
;       float* yb = ybuf + (c & 1) * 2048 + row16 * 4 + (kp >> 2);
;       const int vofs = 320 + rq * 16 + row16 - kp * 4;
;       f32x4 kkA, wA, kaA, kA, rA, kkB, wB, kaB, kB, rB; float vA, vB;
;       RW_LD(0, A)
; #pragma unroll 2
;       for (int s = 0; s < 32; s += 2) {
;         RW_LD(s + 1, B)
;         __builtin_amdgcn_sched_barrier(0);
;         RW_STEP(s, A)
;         __builtin_amdgcn_sched_barrier(0);
;         if (s + 2 < 32) RW_LD(s + 2, A)
;         __builtin_amdgcn_sched_barrier(0);
;         RW_STEP(s + 1, B)
;         __builtin_amdgcn_sched_barrier(0);
;       }
	v_pk_mul_f32 v[104:105], v[100:101], v[24:25]
	v_add_f32_e32 v106, v106, v107
	ds_read_b128 v[84:87], v98 offset:33280
	v_pk_fma_f32 v[104:105], v[102:103], v[26:27], v[104:105]
	v_add_f32_dpp v106, v106, v106 quad_perm:[1,0,3,2] row_mask:0xf bank_mask:0xf bound_ctrl:1
	v_add_f32_e32 v104, v104, v105
	s_nop 0
	v_add_f32_dpp v106, v106, v106 quad_perm:[2,3,0,1] row_mask:0xf bank_mask:0xf bound_ctrl:1
	ds_write_b32 v97, v106 offset:5120
	ds_read_b32 v22, v99 offset:35072
	ds_read_b128 v[14:17], v98 offset:34560
	v_add_f32_dpp v104, v104, v104 quad_perm:[1,0,3,2] row_mask:0xf bank_mask:0xf bound_ctrl:1
	ds_read_b128 v[2:5], v98 offset:33792
	ds_read_b128 v[6:9], v98 offset:34048
	v_add_f32_dpp v104, v104, v104 quad_perm:[2,3,0,1] row_mask:0xf bank_mask:0xf bound_ctrl:1
	v_pk_mul_f32 v[36:37], v[36:37], v[40:41] op_sel_hi:[1,0]
	v_pk_mul_f32 v[38:39], v[38:39], v[40:41] op_sel_hi:[1,0]
	v_add_f32_dpp v104, v104, v104 row_half_mirror row_mask:0xf bank_mask:0xf bound_ctrl:1
	s_waitcnt lgkmcnt(5)
	v_pk_fma_f32 v[36:37], v[100:101], v[28:29], v[36:37]
	v_pk_fma_f32 v[38:39], v[102:103], v[30:31], v[38:39]
	v_add_f32_dpp v104, v104, v104 row_mirror row_mask:0xf bank_mask:0xf bound_ctrl:1
	v_pk_fma_f32 v[100:101], v[32:33], v[104:105], v[36:37] op_sel_hi:[1,0,1] neg_lo:[0,1,0] neg_hi:[0,1,0]
	v_pk_fma_f32 v[102:103], v[34:35], v[104:105], v[38:39] op_sel_hi:[1,0,1] neg_lo:[0,1,0] neg_hi:[0,1,0]
	v_pk_mul_f32 v[106:107], v[100:101], v[84:85]
	ds_read_b128 v[10:13], v98 offset:34304
	v_pk_fma_f32 v[106:107], v[102:103], v[86:87], v[106:107]
	s_waitcnt lgkmcnt(2)
	v_pk_mul_f32 v[104:105], v[100:101], v[2:3]
	v_add_f32_e32 v106, v106, v107
	ds_read_b128 v[18:21], v98 offset:34816
	v_pk_fma_f32 v[104:105], v[102:103], v[4:5], v[104:105]
	v_add_f32_dpp v106, v106, v106 quad_perm:[1,0,3,2] row_mask:0xf bank_mask:0xf bound_ctrl:1
	v_add_f32_e32 v104, v104, v105
	s_nop 0
	v_add_f32_dpp v106, v106, v106 quad_perm:[2,3,0,1] row_mask:0xf bank_mask:0xf bound_ctrl:1
	ds_write_b32 v97, v106 offset:5376
	ds_read_b32 v40, v99 offset:36608
	ds_read_b128 v[36:39], v98 offset:36096
	v_add_f32_dpp v104, v104, v104 quad_perm:[1,0,3,2] row_mask:0xf bank_mask:0xf bound_ctrl:1
	ds_read_b128 v[24:27], v98 offset:35328
	ds_read_b128 v[28:31], v98 offset:35584
	v_add_f32_dpp v104, v104, v104 quad_perm:[2,3,0,1] row_mask:0xf bank_mask:0xf bound_ctrl:1
	v_pk_mul_f32 v[14:15], v[14:15], v[22:23] op_sel_hi:[1,0]
	v_pk_mul_f32 v[16:17], v[16:17], v[22:23] op_sel_hi:[1,0]
	v_add_f32_dpp v104, v104, v104 row_half_mirror row_mask:0xf bank_mask:0xf bound_ctrl:1
	s_waitcnt lgkmcnt(5)
	v_pk_fma_f32 v[14:15], v[100:101], v[6:7], v[14:15]
	v_pk_fma_f32 v[16:17], v[102:103], v[8:9], v[16:17]
	v_add_f32_dpp v104, v104, v104 row_mirror row_mask:0xf bank_mask:0xf bound_ctrl:1
	v_pk_fma_f32 v[100:101], v[10:11], v[104:105], v[14:15] op_sel_hi:[1,0,1] neg_lo:[0,1,0] neg_hi:[0,1,0]
	v_pk_fma_f32 v[102:103], v[12:13], v[104:105], v[16:17] op_sel_hi:[1,0,1] neg_lo:[0,1,0] neg_hi:[0,1,0]
	v_pk_mul_f32 v[106:107], v[100:101], v[18:19]
	ds_read_b128 v[32:35], v98 offset:35840
	v_pk_fma_f32 v[106:107], v[102:103], v[20:21], v[106:107]
	s_waitcnt lgkmcnt(2)
	v_pk_mul_f32 v[104:105], v[100:101], v[24:25]
	v_add_f32_e32 v106, v106, v107
	ds_read_b128 v[84:87], v98 offset:36352
	v_pk_fma_f32 v[104:105], v[102:103], v[26:27], v[104:105]
	v_add_f32_dpp v106, v106, v106 quad_perm:[1,0,3,2] row_mask:0xf bank_mask:0xf bound_ctrl:1
	v_add_f32_e32 v104, v104, v105
	s_nop 0
	v_add_f32_dpp v106, v106, v106 quad_perm:[2,3,0,1] row_mask:0xf bank_mask:0xf bound_ctrl:1
	ds_write_b32 v97, v106 offset:5632
	ds_read_b32 v22, v99 offset:38144
	ds_read_b128 v[14:17], v98 offset:37632
	v_add_f32_dpp v104, v104, v104 quad_perm:[1,0,3,2] row_mask:0xf bank_mask:0xf bound_ctrl:1
	ds_read_b128 v[2:5], v98 offset:36864
	ds_read_b128 v[6:9], v98 offset:37120
	v_add_f32_dpp v104, v104, v104 quad_perm:[2,3,0,1] row_mask:0xf bank_mask:0xf bound_ctrl:1
	v_pk_mul_f32 v[36:37], v[36:37], v[40:41] op_sel_hi:[1,0]
	v_pk_mul_f32 v[38:39], v[38:39], v[40:41] op_sel_hi:[1,0]
	v_add_f32_dpp v104, v104, v104 row_half_mirror row_mask:0xf bank_mask:0xf bound_ctrl:1
	s_waitcnt lgkmcnt(5)
	v_pk_fma_f32 v[36:37], v[100:101], v[28:29], v[36:37]
	v_pk_fma_f32 v[38:39], v[102:103], v[30:31], v[38:39]
	v_add_f32_dpp v104, v104, v104 row_mirror row_mask:0xf bank_mask:0xf bound_ctrl:1
	v_pk_fma_f32 v[100:101], v[32:33], v[104:105], v[36:37] op_sel_hi:[1,0,1] neg_lo:[0,1,0] neg_hi:[0,1,0]
	v_pk_fma_f32 v[102:103], v[34:35], v[104:105], v[38:39] op_sel_hi:[1,0,1] neg_lo:[0,1,0] neg_hi:[0,1,0]
	v_pk_mul_f32 v[106:107], v[100:101], v[84:85]
	ds_read_b128 v[10:13], v98 offset:37376
	v_pk_fma_f32 v[106:107], v[102:103], v[86:87], v[106:107]
	s_waitcnt lgkmcnt(2)
	v_pk_mul_f32 v[104:105], v[100:101], v[2:3]
	v_add_f32_e32 v106, v106, v107
	ds_read_b128 v[18:21], v98 offset:37888
	v_pk_fma_f32 v[104:105], v[102:103], v[4:5], v[104:105]
	v_add_f32_dpp v106, v106, v106 quad_perm:[1,0,3,2] row_mask:0xf bank_mask:0xf bound_ctrl:1
	v_add_f32_e32 v104, v104, v105
	s_nop 0
	v_add_f32_dpp v106, v106, v106 quad_perm:[2,3,0,1] row_mask:0xf bank_mask:0xf bound_ctrl:1
	ds_write_b32 v97, v106 offset:5888
	ds_read_b32 v40, v99 offset:39680
	ds_read_b128 v[36:39], v98 offset:39168
	v_add_f32_dpp v104, v104, v104 quad_perm:[1,0,3,2] row_mask:0xf bank_mask:0xf bound_ctrl:1
	ds_read_b128 v[24:27], v98 offset:38400
	ds_read_b128 v[28:31], v98 offset:38656
	v_add_f32_dpp v104, v104, v104 quad_perm:[2,3,0,1] row_mask:0xf bank_mask:0xf bound_ctrl:1
	v_pk_mul_f32 v[14:15], v[14:15], v[22:23] op_sel_hi:[1,0]
	v_pk_mul_f32 v[16:17], v[16:17], v[22:23] op_sel_hi:[1,0]
	v_add_f32_dpp v104, v104, v104 row_half_mirror row_mask:0xf bank_mask:0xf bound_ctrl:1
	s_waitcnt lgkmcnt(5)
; DEVI void rwkv_scan_item(const Params& p, const int item, char* smem) {
;     ...
;   for (int c = 0; c < NC; ++c) {
;     if (wid >= 4) {
;       if (c + 1 < NC) load_chunk(c + 1, (c + 1) & 1);
;       if (c >= 1) store_y(c - 1);
;     } else {
;       const float* sb = buf + (c & 1) * 12288 + kp * 4;
;       float* yb = ybuf + (c & 1) * 2048 + row16 * 4 + (kp >> 2);
;       const int vofs = 320 + rq * 16 + row16 - kp * 4;
;       f32x4 kkA, wA, kaA, kA, rA, kkB, wB, kaB, kB, rB; float vA, vB;
;       RW_LD(0, A)
; #pragma unroll 2
;       for (int s = 0; s < 32; s += 2) {
;         RW_LD(s + 1, B)
;         __builtin_amdgcn_sched_barrier(0);
;         RW_STEP(s, A)
;         __builtin_amdgcn_sched_barrier(0);
;         if (s + 2 < 32) RW_LD(s + 2, A)
;         __builtin_amdgcn_sched_barrier(0);
;         RW_STEP(s + 1, B)
;         __builtin_amdgcn_sched_barrier(0);
;       }
	v_pk_fma_f32 v[14:15], v[100:101], v[6:7], v[14:15]
	v_pk_fma_f32 v[16:17], v[102:103], v[8:9], v[16:17]
	v_add_f32_dpp v104, v104, v104 row_mirror row_mask:0xf bank_mask:0xf bound_ctrl:1
	v_pk_fma_f32 v[100:101], v[10:11], v[104:105], v[14:15] op_sel_hi:[1,0,1] neg_lo:[0,1,0] neg_hi:[0,1,0]
	v_pk_fma_f32 v[102:103], v[12:13], v[104:105], v[16:17] op_sel_hi:[1,0,1] neg_lo:[0,1,0] neg_hi:[0,1,0]
	v_pk_mul_f32 v[106:107], v[100:101], v[18:19]
	ds_read_b128 v[32:35], v98 offset:38912
	v_pk_fma_f32 v[106:107], v[102:103], v[20:21], v[106:107]
	s_waitcnt lgkmcnt(2)
	v_pk_mul_f32 v[104:105], v[100:101], v[24:25]
	v_add_f32_e32 v106, v106, v107
	ds_read_b128 v[84:87], v98 offset:39424
	v_pk_fma_f32 v[104:105], v[102:103], v[26:27], v[104:105]
	v_add_f32_dpp v106, v106, v106 quad_perm:[1,0,3,2] row_mask:0xf bank_mask:0xf bound_ctrl:1
	v_add_f32_e32 v104, v104, v105
	s_nop 0
	v_add_f32_dpp v106, v106, v106 quad_perm:[2,3,0,1] row_mask:0xf bank_mask:0xf bound_ctrl:1
	ds_write_b32 v97, v106 offset:6144
	ds_read_b32 v22, v99 offset:41216
	ds_read_b128 v[14:17], v98 offset:40704
	v_add_f32_dpp v104, v104, v104 quad_perm:[1,0,3,2] row_mask:0xf bank_mask:0xf bound_ctrl:1
	ds_read_b128 v[2:5], v98 offset:39936
	ds_read_b128 v[6:9], v98 offset:40192
	v_add_f32_dpp v104, v104, v104 quad_perm:[2,3,0,1] row_mask:0xf bank_mask:0xf bound_ctrl:1
	v_pk_mul_f32 v[36:37], v[36:37], v[40:41] op_sel_hi:[1,0]
	v_pk_mul_f32 v[38:39], v[38:39], v[40:41] op_sel_hi:[1,0]
	v_add_f32_dpp v104, v104, v104 row_half_mirror row_mask:0xf bank_mask:0xf bound_ctrl:1
	s_waitcnt lgkmcnt(5)
	v_pk_fma_f32 v[36:37], v[100:101], v[28:29], v[36:37]
	v_pk_fma_f32 v[38:39], v[102:103], v[30:31], v[38:39]
	v_add_f32_dpp v104, v104, v104 row_mirror row_mask:0xf bank_mask:0xf bound_ctrl:1
	v_pk_fma_f32 v[100:101], v[32:33], v[104:105], v[36:37] op_sel_hi:[1,0,1] neg_lo:[0,1,0] neg_hi:[0,1,0]
	v_pk_fma_f32 v[102:103], v[34:35], v[104:105], v[38:39] op_sel_hi:[1,0,1] neg_lo:[0,1,0] neg_hi:[0,1,0]
	v_pk_mul_f32 v[106:107], v[100:101], v[84:85]
	ds_read_b128 v[10:13], v98 offset:40448
	v_pk_fma_f32 v[106:107], v[102:103], v[86:87], v[106:107]
	s_waitcnt lgkmcnt(2)
	v_pk_mul_f32 v[104:105], v[100:101], v[2:3]
	v_add_f32_e32 v106, v106, v107
	ds_read_b128 v[18:21], v98 offset:40960
	v_pk_fma_f32 v[104:105], v[102:103], v[4:5], v[104:105]
	v_add_f32_dpp v106, v106, v106 quad_perm:[1,0,3,2] row_mask:0xf bank_mask:0xf bound_ctrl:1
	v_add_f32_e32 v104, v104, v105
	s_nop 0
	v_add_f32_dpp v106, v106, v106 quad_perm:[2,3,0,1] row_mask:0xf bank_mask:0xf bound_ctrl:1
	ds_write_b32 v97, v106 offset:6400
	ds_read_b32 v40, v99 offset:42752
	ds_read_b128 v[36:39], v98 offset:42240
	v_add_f32_dpp v104, v104, v104 quad_perm:[1,0,3,2] row_mask:0xf bank_mask:0xf bound_ctrl:1
	ds_read_b128 v[24:27], v98 offset:41472
	ds_read_b128 v[28:31], v98 offset:41728
	v_add_f32_dpp v104, v104, v104 quad_perm:[2,3,0,1] row_mask:0xf bank_mask:0xf bound_ctrl:1
	v_pk_mul_f32 v[14:15], v[14:15], v[22:23] op_sel_hi:[1,0]
	v_pk_mul_f32 v[16:17], v[16:17], v[22:23] op_sel_hi:[1,0]
	v_add_f32_dpp v104, v104, v104 row_half_mirror row_mask:0xf bank_mask:0xf bound_ctrl:1
	s_waitcnt lgkmcnt(5)
	v_pk_fma_f32 v[14:15], v[100:101], v[6:7], v[14:15]
	v_pk_fma_f32 v[16:17], v[102:103], v[8:9], v[16:17]
	v_add_f32_dpp v104, v104, v104 row_mirror row_mask:0xf bank_mask:0xf bound_ctrl:1
	v_pk_fma_f32 v[100:101], v[10:11], v[104:105], v[14:15] op_sel_hi:[1,0,1] neg_lo:[0,1,0] neg_hi:[0,1,0]
	v_pk_fma_f32 v[102:103], v[12:13], v[104:105], v[16:17] op_sel_hi:[1,0,1] neg_lo:[0,1,0] neg_hi:[0,1,0]
	v_pk_mul_f32 v[106:107], v[100:101], v[18:19]
	ds_read_b128 v[32:35], v98 offset:41984
	v_pk_fma_f32 v[106:107], v[102:103], v[20:21], v[106:107]
	s_waitcnt lgkmcnt(2)
	v_pk_mul_f32 v[104:105], v[100:101], v[24:25]
	v_add_f32_e32 v106, v106, v107
	ds_read_b128 v[84:87], v98 offset:42496
	v_pk_fma_f32 v[104:105], v[102:103], v[26:27], v[104:105]
	v_add_f32_dpp v106, v106, v106 quad_perm:[1,0,3,2] row_mask:0xf bank_mask:0xf bound_ctrl:1
	v_add_f32_e32 v104, v104, v105
	s_nop 0
	v_add_f32_dpp v106, v106, v106 quad_perm:[2,3,0,1] row_mask:0xf bank_mask:0xf bound_ctrl:1
	ds_write_b32 v97, v106 offset:6656
	ds_read_b32 v22, v99 offset:44288
	ds_read_b128 v[14:17], v98 offset:43776
	v_add_f32_dpp v104, v104, v104 quad_perm:[1,0,3,2] row_mask:0xf bank_mask:0xf bound_ctrl:1
	ds_read_b128 v[2:5], v98 offset:43008
	ds_read_b128 v[6:9], v98 offset:43264
	v_add_f32_dpp v104, v104, v104 quad_perm:[2,3,0,1] row_mask:0xf bank_mask:0xf bound_ctrl:1
	v_pk_mul_f32 v[36:37], v[36:37], v[40:41] op_sel_hi:[1,0]
	v_pk_mul_f32 v[38:39], v[38:39], v[40:41] op_sel_hi:[1,0]
	v_add_f32_dpp v104, v104, v104 row_half_mirror row_mask:0xf bank_mask:0xf bound_ctrl:1
	s_waitcnt lgkmcnt(5)
	v_pk_fma_f32 v[36:37], v[100:101], v[28:29], v[36:37]
	v_pk_fma_f32 v[38:39], v[102:103], v[30:31], v[38:39]
	v_add_f32_dpp v104, v104, v104 row_mirror row_mask:0xf bank_mask:0xf bound_ctrl:1
	v_pk_fma_f32 v[100:101], v[32:33], v[104:105], v[36:37] op_sel_hi:[1,0,1] neg_lo:[0,1,0] neg_hi:[0,1,0]
	v_pk_fma_f32 v[102:103], v[34:35], v[104:105], v[38:39] op_sel_hi:[1,0,1] neg_lo:[0,1,0] neg_hi:[0,1,0]
	v_pk_mul_f32 v[106:107], v[100:101], v[84:85]
	ds_read_b128 v[10:13], v98 offset:43520
	v_pk_fma_f32 v[106:107], v[102:103], v[86:87], v[106:107]
	s_waitcnt lgkmcnt(2)
; DEVI void rwkv_scan_item(const Params& p, const int item, char* smem) {
;     ...
; #pragma unroll 2
;       for (int s = 0; s < 32; s += 2) {
;         RW_LD(s + 1, B)
;         __builtin_amdgcn_sched_barrier(0);
;         RW_STEP(s, A)
;         __builtin_amdgcn_sched_barrier(0);
;         if (s + 2 < 32) RW_LD(s + 2, A)
;         __builtin_amdgcn_sched_barrier(0);
;         RW_STEP(s + 1, B)
;         __builtin_amdgcn_sched_barrier(0);
;       }
	v_pk_mul_f32 v[104:105], v[100:101], v[2:3]
	v_add_f32_e32 v106, v106, v107
	ds_read_b128 v[18:21], v98 offset:44032
	v_pk_fma_f32 v[104:105], v[102:103], v[4:5], v[104:105]
	v_add_f32_dpp v106, v106, v106 quad_perm:[1,0,3,2] row_mask:0xf bank_mask:0xf bound_ctrl:1
	v_add_f32_e32 v104, v104, v105
	s_nop 0
	v_add_f32_dpp v106, v106, v106 quad_perm:[2,3,0,1] row_mask:0xf bank_mask:0xf bound_ctrl:1
	ds_write_b32 v97, v106 offset:6912
	ds_read_b32 v40, v99 offset:45824
	ds_read_b128 v[36:39], v98 offset:45312
	v_add_f32_dpp v104, v104, v104 quad_perm:[1,0,3,2] row_mask:0xf bank_mask:0xf bound_ctrl:1
	ds_read_b128 v[24:27], v98 offset:44544
	ds_read_b128 v[28:31], v98 offset:44800
	v_add_f32_dpp v104, v104, v104 quad_perm:[2,3,0,1] row_mask:0xf bank_mask:0xf bound_ctrl:1
	v_pk_mul_f32 v[14:15], v[14:15], v[22:23] op_sel_hi:[1,0]
	v_pk_mul_f32 v[16:17], v[16:17], v[22:23] op_sel_hi:[1,0]
	v_add_f32_dpp v104, v104, v104 row_half_mirror row_mask:0xf bank_mask:0xf bound_ctrl:1
	s_waitcnt lgkmcnt(5)
	v_pk_fma_f32 v[14:15], v[100:101], v[6:7], v[14:15]
	v_pk_fma_f32 v[16:17], v[102:103], v[8:9], v[16:17]
	v_add_f32_dpp v104, v104, v104 row_mirror row_mask:0xf bank_mask:0xf bound_ctrl:1
	v_pk_fma_f32 v[100:101], v[10:11], v[104:105], v[14:15] op_sel_hi:[1,0,1] neg_lo:[0,1,0] neg_hi:[0,1,0]
	v_pk_fma_f32 v[102:103], v[12:13], v[104:105], v[16:17] op_sel_hi:[1,0,1] neg_lo:[0,1,0] neg_hi:[0,1,0]
	v_pk_mul_f32 v[106:107], v[100:101], v[18:19]
	ds_read_b128 v[32:35], v98 offset:45056
	v_pk_fma_f32 v[106:107], v[102:103], v[20:21], v[106:107]
	s_waitcnt lgkmcnt(2)
	v_pk_mul_f32 v[104:105], v[100:101], v[24:25]
	v_add_f32_e32 v106, v106, v107
	ds_read_b128 v[84:87], v98 offset:45568
	v_pk_fma_f32 v[104:105], v[102:103], v[26:27], v[104:105]
	v_add_f32_dpp v106, v106, v106 quad_perm:[1,0,3,2] row_mask:0xf bank_mask:0xf bound_ctrl:1
	v_add_f32_e32 v104, v104, v105
	s_nop 0
	v_add_f32_dpp v106, v106, v106 quad_perm:[2,3,0,1] row_mask:0xf bank_mask:0xf bound_ctrl:1
	ds_write_b32 v97, v106 offset:7168
	ds_read_b32 v22, v99 offset:47360
	ds_read_b128 v[14:17], v98 offset:46848
	v_add_f32_dpp v104, v104, v104 quad_perm:[1,0,3,2] row_mask:0xf bank_mask:0xf bound_ctrl:1
	ds_read_b128 v[2:5], v98 offset:46080
	ds_read_b128 v[6:9], v98 offset:46336
	v_add_f32_dpp v104, v104, v104 quad_perm:[2,3,0,1] row_mask:0xf bank_mask:0xf bound_ctrl:1
	v_pk_mul_f32 v[36:37], v[36:37], v[40:41] op_sel_hi:[1,0]
	v_pk_mul_f32 v[38:39], v[38:39], v[40:41] op_sel_hi:[1,0]
	v_add_f32_dpp v104, v104, v104 row_half_mirror row_mask:0xf bank_mask:0xf bound_ctrl:1
	s_waitcnt lgkmcnt(5)
	v_pk_fma_f32 v[36:37], v[100:101], v[28:29], v[36:37]
	v_pk_fma_f32 v[38:39], v[102:103], v[30:31], v[38:39]
	v_add_f32_dpp v104, v104, v104 row_mirror row_mask:0xf bank_mask:0xf bound_ctrl:1
	v_pk_fma_f32 v[100:101], v[32:33], v[104:105], v[36:37] op_sel_hi:[1,0,1] neg_lo:[0,1,0] neg_hi:[0,1,0]
	v_pk_fma_f32 v[102:103], v[34:35], v[104:105], v[38:39] op_sel_hi:[1,0,1] neg_lo:[0,1,0] neg_hi:[0,1,0]
	v_pk_mul_f32 v[106:107], v[100:101], v[84:85]
	ds_read_b128 v[10:13], v98 offset:46592
	v_pk_fma_f32 v[106:107], v[102:103], v[86:87], v[106:107]
	s_waitcnt lgkmcnt(2)
	v_pk_mul_f32 v[104:105], v[100:101], v[2:3]
	v_add_f32_e32 v106, v106, v107
	ds_read_b128 v[18:21], v98 offset:47104
	v_pk_fma_f32 v[104:105], v[102:103], v[4:5], v[104:105]
	v_add_f32_dpp v106, v106, v106 quad_perm:[1,0,3,2] row_mask:0xf bank_mask:0xf bound_ctrl:1
	v_add_f32_e32 v104, v104, v105
	s_nop 0
	v_add_f32_dpp v106, v106, v106 quad_perm:[2,3,0,1] row_mask:0xf bank_mask:0xf bound_ctrl:1
	ds_write_b32 v97, v106 offset:7424
	ds_read_b32 v40, v99 offset:48896
	ds_read_b128 v[36:39], v98 offset:48384
	v_add_f32_dpp v104, v104, v104 quad_perm:[1,0,3,2] row_mask:0xf bank_mask:0xf bound_ctrl:1
	ds_read_b128 v[24:27], v98 offset:47616
	ds_read_b128 v[28:31], v98 offset:47872
	v_add_f32_dpp v104, v104, v104 quad_perm:[2,3,0,1] row_mask:0xf bank_mask:0xf bound_ctrl:1
	v_pk_mul_f32 v[14:15], v[14:15], v[22:23] op_sel_hi:[1,0]
	v_pk_mul_f32 v[16:17], v[16:17], v[22:23] op_sel_hi:[1,0]
	v_add_f32_dpp v104, v104, v104 row_half_mirror row_mask:0xf bank_mask:0xf bound_ctrl:1
	s_waitcnt lgkmcnt(5)
	v_pk_fma_f32 v[14:15], v[100:101], v[6:7], v[14:15]
	v_pk_fma_f32 v[16:17], v[102:103], v[8:9], v[16:17]
	v_add_f32_dpp v104, v104, v104 row_mirror row_mask:0xf bank_mask:0xf bound_ctrl:1
	v_pk_fma_f32 v[100:101], v[10:11], v[104:105], v[14:15] op_sel_hi:[1,0,1] neg_lo:[0,1,0] neg_hi:[0,1,0]
	v_pk_fma_f32 v[102:103], v[12:13], v[104:105], v[16:17] op_sel_hi:[1,0,1] neg_lo:[0,1,0] neg_hi:[0,1,0]
	v_pk_mul_f32 v[106:107], v[100:101], v[18:19]
	ds_read_b128 v[32:35], v98 offset:48128
	v_pk_fma_f32 v[106:107], v[102:103], v[20:21], v[106:107]
	s_waitcnt lgkmcnt(2)
	v_pk_mul_f32 v[104:105], v[100:101], v[24:25]
	v_add_f32_e32 v106, v106, v107
	ds_read_b128 v[84:87], v98 offset:48640
	v_pk_fma_f32 v[104:105], v[102:103], v[26:27], v[104:105]
	v_add_f32_dpp v106, v106, v106 quad_perm:[1,0,3,2] row_mask:0xf bank_mask:0xf bound_ctrl:1
	v_add_f32_e32 v104, v104, v105
	s_nop 0
	v_add_f32_dpp v106, v106, v106 quad_perm:[2,3,0,1] row_mask:0xf bank_mask:0xf bound_ctrl:1
	ds_write_b32 v97, v106 offset:7680
	v_add_f32_dpp v104, v104, v104 quad_perm:[1,0,3,2] row_mask:0xf bank_mask:0xf bound_ctrl:1
	v_pk_mul_f32 v[36:37], v[36:37], v[40:41] op_sel_hi:[1,0]
	v_pk_mul_f32 v[38:39], v[38:39], v[40:41] op_sel_hi:[1,0]
	v_add_f32_dpp v104, v104, v104 quad_perm:[2,3,0,1] row_mask:0xf bank_mask:0xf bound_ctrl:1
	s_waitcnt lgkmcnt(1)
	v_pk_fma_f32 v[36:37], v[100:101], v[28:29], v[36:37]
	v_pk_fma_f32 v[38:39], v[102:103], v[30:31], v[38:39]
	v_add_f32_dpp v104, v104, v104 row_half_mirror row_mask:0xf bank_mask:0xf bound_ctrl:1
	s_nop 1
	v_add_f32_dpp v104, v104, v104 row_mirror row_mask:0xf bank_mask:0xf bound_ctrl:1
	v_pk_fma_f32 v[100:101], v[32:33], v[104:105], v[36:37] op_sel_hi:[1,0,1] neg_lo:[0,1,0] neg_hi:[0,1,0]
	v_pk_fma_f32 v[102:103], v[34:35], v[104:105], v[38:39] op_sel_hi:[1,0,1] neg_lo:[0,1,0] neg_hi:[0,1,0]
	v_pk_mul_f32 v[106:107], v[100:101], v[84:85]
	s_nop 0
	v_pk_fma_f32 v[106:107], v[102:103], v[86:87], v[106:107]
	s_nop 0
	v_add_f32_e32 v106, v106, v107
	s_nop 1
	v_add_f32_dpp v106, v106, v106 quad_perm:[1,0,3,2] row_mask:0xf bank_mask:0xf bound_ctrl:1
	s_nop 1
	v_add_f32_dpp v106, v106, v106 quad_perm:[2,3,0,1] row_mask:0xf bank_mask:0xf bound_ctrl:1
	ds_write_b32 v97, v106 offset:7936

;     ...
;   if (cidx != 1 && cidx != 3) for (int it = blockIdx.x; it < 96; it += gridDim.x) rwkv_scan_item(p, it, smem);
;   if (cidx == 2) return;
;   float d1 = 0.f, d2 = 0.f;
;   for (int i = 0; i < 64; ++i) { d1 += p.in[25][l * 64 + i] * p.in[26][l * 64 + i]; d2 += p.in[27][l * 64 + i] * p.in[28][l * 64 + i]; }
.LBB0_526:
	s_setprio 0
	v_mov_b32_e32 v1, 0
	v_readlane_b32 s12, v252, 0
	s_mov_b64 s[0:1], 0
	v_mov_b32_e32 v2, 0
	v_mov_b32_e32 v3, v1
	v_readlane_b32 s14, v252, 2
	v_readlane_b32 s15, v252, 3
	v_readlane_b32 s16, v252, 4
	v_readlane_b32 s17, v252, 5
	v_readlane_b32 s18, v252, 6
	v_readlane_b32 s19, v252, 7
	v_readlane_b32 s20, v252, 8
	v_readlane_b32 s21, v252, 9
	v_readlane_b32 s22, v252, 10
	v_readlane_b32 s23, v252, 11
	v_readlane_b32 s13, v252, 1
	v_readlane_b32 s24, v252, 12
	v_readlane_b32 s25, v252, 13
	v_readlane_b32 s26, v252, 14
	v_readlane_b32 s27, v252, 15

; DEVI void rwkv_scan_item(const Params& p, const int item, char* smem) {
;     ...
;       const float* sb = buf + (c & 1) * 12288 + kp * 4;
;       float* yb = ybuf + (c & 1) * 2048 + row16 * 4 + (kp >> 2);
;       const int vofs = 320 + rq * 16 + row16 - kp * 4;
.LBB0_1290:
	s_and_saveexec_b64 s[58:59], s[2:3]
	s_xor_b64 s[58:59], exec, s[58:59]
	s_cbranch_execz .LBB0_1295
	s_setprio 3
	s_and_b32 s52, s65, 1
	s_mul_i32 s52, s52, 0xc000
	v_add_u32_e32 v98, s52, v83
	ds_read_b128 v[2:5], v98
	v_lshl_add_u32 v99, v63, 2, v98
	ds_read_b32 v22, v99 offset:1280
	ds_read_b128 v[14:17], v98 offset:768
	ds_read_b128 v[6:9], v98 offset:256
	ds_read_b128 v[10:13], v98 offset:512
	ds_read_b128 v[18:21], v98 offset:1024
	s_and_b32 s52, s65, 1
	s_lshl_b32 s52, s52, 13
	s_add_i32 s52, s52, 0x18010
	v_add_u32_e32 v97, s52, v94
	s_waitcnt lgkmcnt(0)
	v_pk_mul_f32 v[104:105], v[100:101], v[2:3]
	s_nop 0
	v_pk_fma_f32 v[104:105], v[102:103], v[4:5], v[104:105]
	s_nop 0
	v_add_f32_e32 v104, v104, v105
	ds_read_b32 v40, v99 offset:2816
	ds_read_b128 v[36:39], v98 offset:2304
	v_add_f32_dpp v104, v104, v104 quad_perm:[1,0,3,2] row_mask:0xf bank_mask:0xf bound_ctrl:1
	ds_read_b128 v[24:27], v98 offset:1536
	ds_read_b128 v[28:31], v98 offset:1792
	v_add_f32_dpp v104, v104, v104 quad_perm:[2,3,0,1] row_mask:0xf bank_mask:0xf bound_ctrl:1
	v_pk_mul_f32 v[14:15], v[14:15], v[22:23] op_sel_hi:[1,0]
	v_pk_mul_f32 v[16:17], v[16:17], v[22:23] op_sel_hi:[1,0]
	v_add_f32_dpp v104, v104, v104 row_half_mirror row_mask:0xf bank_mask:0xf bound_ctrl:1
	s_waitcnt lgkmcnt(5)
	v_pk_fma_f32 v[14:15], v[100:101], v[6:7], v[14:15]
	v_pk_fma_f32 v[16:17], v[102:103], v[8:9], v[16:17]
	v_add_f32_dpp v104, v104, v104 row_mirror row_mask:0xf bank_mask:0xf bound_ctrl:1
	v_pk_fma_f32 v[100:101], v[10:11], v[104:105], v[14:15] op_sel_hi:[1,0,1] neg_lo:[0,1,0] neg_hi:[0,1,0]
	v_pk_fma_f32 v[102:103], v[12:13], v[104:105], v[16:17] op_sel_hi:[1,0,1] neg_lo:[0,1,0] neg_hi:[0,1,0]
	v_pk_mul_f32 v[106:107], v[100:101], v[18:19]
	ds_read_b128 v[32:35], v98 offset:2048
	v_pk_fma_f32 v[106:107], v[102:103], v[20:21], v[106:107]
	s_waitcnt lgkmcnt(2)
	v_pk_mul_f32 v[104:105], v[100:101], v[24:25]
	v_add_f32_e32 v106, v106, v107
	ds_read_b128 v[84:87], v98 offset:2560
	v_pk_fma_f32 v[104:105], v[102:103], v[26:27], v[104:105]
	v_add_f32_dpp v106, v106, v106 quad_perm:[1,0,3,2] row_mask:0xf bank_mask:0xf bound_ctrl:1
	v_add_f32_e32 v104, v104, v105
	s_nop 0
	v_add_f32_dpp v106, v106, v106 quad_perm:[2,3,0,1] row_mask:0xf bank_mask:0xf bound_ctrl:1
	ds_write_b32 v97, v106 offset:0
	ds_read_b32 v22, v99 offset:4352
	ds_read_b128 v[14:17], v98 offset:3840
	v_add_f32_dpp v104, v104, v104 quad_perm:[1,0,3,2] row_mask:0xf bank_mask:0xf bound_ctrl:1
	ds_read_b128 v[2:5], v98 offset:3072
	ds_read_b128 v[6:9], v98 offset:3328
	v_add_f32_dpp v104, v104, v104 quad_perm:[2,3,0,1] row_mask:0xf bank_mask:0xf bound_ctrl:1
	v_pk_mul_f32 v[36:37], v[36:37], v[40:41] op_sel_hi:[1,0]
	v_pk_mul_f32 v[38:39], v[38:39], v[40:41] op_sel_hi:[1,0]
	v_add_f32_dpp v104, v104, v104 row_half_mirror row_mask:0xf bank_mask:0xf bound_ctrl:1
	s_waitcnt lgkmcnt(5)
	v_pk_fma_f32 v[36:37], v[100:101], v[28:29], v[36:37]
	v_pk_fma_f32 v[38:39], v[102:103], v[30:31], v[38:39]
	v_add_f32_dpp v104, v104, v104 row_mirror row_mask:0xf bank_mask:0xf bound_ctrl:1
	v_pk_fma_f32 v[100:101], v[32:33], v[104:105], v[36:37] op_sel_hi:[1,0,1] neg_lo:[0,1,0] neg_hi:[0,1,0]
	v_pk_fma_f32 v[102:103], v[34:35], v[104:105], v[38:39] op_sel_hi:[1,0,1] neg_lo:[0,1,0] neg_hi:[0,1,0]
	v_pk_mul_f32 v[106:107], v[100:101], v[84:85]
	ds_read_b128 v[10:13], v98 offset:3584
	v_pk_fma_f32 v[106:107], v[102:103], v[86:87], v[106:107]
	s_waitcnt lgkmcnt(2)
	v_pk_mul_f32 v[104:105], v[100:101], v[2:3]
	v_add_f32_e32 v106, v106, v107
	ds_read_b128 v[18:21], v98 offset:4096
	v_pk_fma_f32 v[104:105], v[102:103], v[4:5], v[104:105]
	v_add_f32_dpp v106, v106, v106 quad_perm:[1,0,3,2] row_mask:0xf bank_mask:0xf bound_ctrl:1
	v_add_f32_e32 v104, v104, v105
	s_nop 0
	v_add_f32_dpp v106, v106, v106 quad_perm:[2,3,0,1] row_mask:0xf bank_mask:0xf bound_ctrl:1
	ds_write_b32 v97, v106 offset:256
	ds_read_b32 v40, v99 offset:5888
	ds_read_b128 v[36:39], v98 offset:5376
	v_add_f32_dpp v104, v104, v104 quad_perm:[1,0,3,2] row_mask:0xf bank_mask:0xf bound_ctrl:1
	ds_read_b128 v[24:27], v98 offset:4608
	ds_read_b128 v[28:31], v98 offset:4864
	v_add_f32_dpp v104, v104, v104 quad_perm:[2,3,0,1] row_mask:0xf bank_mask:0xf bound_ctrl:1
	v_pk_mul_f32 v[14:15], v[14:15], v[22:23] op_sel_hi:[1,0]
	v_pk_mul_f32 v[16:17], v[16:17], v[22:23] op_sel_hi:[1,0]
	v_add_f32_dpp v104, v104, v104 row_half_mirror row_mask:0xf bank_mask:0xf bound_ctrl:1
	s_waitcnt lgkmcnt(5)
	v_pk_fma_f32 v[14:15], v[100:101], v[6:7], v[14:15]
	v_pk_fma_f32 v[16:17], v[102:103], v[8:9], v[16:17]
	v_add_f32_dpp v104, v104, v104 row_mirror row_mask:0xf bank_mask:0xf bound_ctrl:1
	v_pk_fma_f32 v[100:101], v[10:11], v[104:105], v[14:15] op_sel_hi:[1,0,1] neg_lo:[0,1,0] neg_hi:[0,1,0]
	v_pk_fma_f32 v[102:103], v[12:13], v[104:105], v[16:17] op_sel_hi:[1,0,1] neg_lo:[0,1,0] neg_hi:[0,1,0]
	v_pk_mul_f32 v[106:107], v[100:101], v[18:19]
	ds_read_b128 v[32:35], v98 offset:5120
	v_pk_fma_f32 v[106:107], v[102:103], v[20:21], v[106:107]
	s_waitcnt lgkmcnt(2)
	v_pk_mul_f32 v[104:105], v[100:101], v[24:25]
	v_add_f32_e32 v106, v106, v107
	ds_read_b128 v[84:87], v98 offset:5632
	v_pk_fma_f32 v[104:105], v[102:103], v[26:27], v[104:105]
	v_add_f32_dpp v106, v106, v106 quad_perm:[1,0,3,2] row_mask:0xf bank_mask:0xf bound_ctrl:1
	v_add_f32_e32 v104, v104, v105
	s_nop 0
	v_add_f32_dpp v106, v106, v106 quad_perm:[2,3,0,1] row_mask:0xf bank_mask:0xf bound_ctrl:1
	ds_write_b32 v97, v106 offset:512
	ds_read_b32 v22, v99 offset:7424
	ds_read_b128 v[14:17], v98 offset:6912
	v_add_f32_dpp v104, v104, v104 quad_perm:[1,0,3,2] row_mask:0xf bank_mask:0xf bound_ctrl:1
	ds_read_b128 v[2:5], v98 offset:6144
	ds_read_b128 v[6:9], v98 offset:6400
	v_add_f32_dpp v104, v104, v104 quad_perm:[2,3,0,1] row_mask:0xf bank_mask:0xf bound_ctrl:1
	v_pk_mul_f32 v[36:37], v[36:37], v[40:41] op_sel_hi:[1,0]
	v_pk_mul_f32 v[38:39], v[38:39], v[40:41] op_sel_hi:[1,0]
	v_add_f32_dpp v104, v104, v104 row_half_mirror row_mask:0xf bank_mask:0xf bound_ctrl:1
	s_waitcnt lgkmcnt(5)
; DEVI void rwkv_scan_item(const Params& p, const int item, char* smem) {
;     ...
; #pragma unroll 2
;       for (int s = 0; s < 32; s += 2) {
;         RW_LD(s + 1, B)
;         __builtin_amdgcn_sched_barrier(0);
;         RW_STEP(s, A)
;         __builtin_amdgcn_sched_barrier(0);
;         if (s + 2 < 32) RW_LD(s + 2, A)
;         __builtin_amdgcn_sched_barrier(0);
;         RW_STEP(s + 1, B)
;         __builtin_amdgcn_sched_barrier(0);
;       }
	v_pk_fma_f32 v[36:37], v[100:101], v[28:29], v[36:37]
	v_pk_fma_f32 v[38:39], v[102:103], v[30:31], v[38:39]
	v_add_f32_dpp v104, v104, v104 row_mirror row_mask:0xf bank_mask:0xf bound_ctrl:1
	v_pk_fma_f32 v[100:101], v[32:33], v[104:105], v[36:37] op_sel_hi:[1,0,1] neg_lo:[0,1,0] neg_hi:[0,1,0]
	v_pk_fma_f32 v[102:103], v[34:35], v[104:105], v[38:39] op_sel_hi:[1,0,1] neg_lo:[0,1,0] neg_hi:[0,1,0]
	v_pk_mul_f32 v[106:107], v[100:101], v[84:85]
	ds_read_b128 v[10:13], v98 offset:6656
	v_pk_fma_f32 v[106:107], v[102:103], v[86:87], v[106:107]
	s_waitcnt lgkmcnt(2)
	v_pk_mul_f32 v[104:105], v[100:101], v[2:3]
	v_add_f32_e32 v106, v106, v107
	ds_read_b128 v[18:21], v98 offset:7168
	v_pk_fma_f32 v[104:105], v[102:103], v[4:5], v[104:105]
	v_add_f32_dpp v106, v106, v106 quad_perm:[1,0,3,2] row_mask:0xf bank_mask:0xf bound_ctrl:1
	v_add_f32_e32 v104, v104, v105
	s_nop 0
	v_add_f32_dpp v106, v106, v106 quad_perm:[2,3,0,1] row_mask:0xf bank_mask:0xf bound_ctrl:1
	ds_write_b32 v97, v106 offset:768
	ds_read_b32 v40, v99 offset:8960
	ds_read_b128 v[36:39], v98 offset:8448
	v_add_f32_dpp v104, v104, v104 quad_perm:[1,0,3,2] row_mask:0xf bank_mask:0xf bound_ctrl:1
	ds_read_b128 v[24:27], v98 offset:7680
	ds_read_b128 v[28:31], v98 offset:7936
	v_add_f32_dpp v104, v104, v104 quad_perm:[2,3,0,1] row_mask:0xf bank_mask:0xf bound_ctrl:1
	v_pk_mul_f32 v[14:15], v[14:15], v[22:23] op_sel_hi:[1,0]
	v_pk_mul_f32 v[16:17], v[16:17], v[22:23] op_sel_hi:[1,0]
	v_add_f32_dpp v104, v104, v104 row_half_mirror row_mask:0xf bank_mask:0xf bound_ctrl:1
	s_waitcnt lgkmcnt(5)
	v_pk_fma_f32 v[14:15], v[100:101], v[6:7], v[14:15]
	v_pk_fma_f32 v[16:17], v[102:103], v[8:9], v[16:17]
	v_add_f32_dpp v104, v104, v104 row_mirror row_mask:0xf bank_mask:0xf bound_ctrl:1
	v_pk_fma_f32 v[100:101], v[10:11], v[104:105], v[14:15] op_sel_hi:[1,0,1] neg_lo:[0,1,0] neg_hi:[0,1,0]
	v_pk_fma_f32 v[102:103], v[12:13], v[104:105], v[16:17] op_sel_hi:[1,0,1] neg_lo:[0,1,0] neg_hi:[0,1,0]
	v_pk_mul_f32 v[106:107], v[100:101], v[18:19]
	ds_read_b128 v[32:35], v98 offset:8192
	v_pk_fma_f32 v[106:107], v[102:103], v[20:21], v[106:107]
	s_waitcnt lgkmcnt(2)
	v_pk_mul_f32 v[104:105], v[100:101], v[24:25]
	v_add_f32_e32 v106, v106, v107
	ds_read_b128 v[84:87], v98 offset:8704
	v_pk_fma_f32 v[104:105], v[102:103], v[26:27], v[104:105]
	v_add_f32_dpp v106, v106, v106 quad_perm:[1,0,3,2] row_mask:0xf bank_mask:0xf bound_ctrl:1
	v_add_f32_e32 v104, v104, v105
	s_nop 0
	v_add_f32_dpp v106, v106, v106 quad_perm:[2,3,0,1] row_mask:0xf bank_mask:0xf bound_ctrl:1
	ds_write_b32 v97, v106 offset:1024
	ds_read_b32 v22, v99 offset:10496
	ds_read_b128 v[14:17], v98 offset:9984
	v_add_f32_dpp v104, v104, v104 quad_perm:[1,0,3,2] row_mask:0xf bank_mask:0xf bound_ctrl:1
	ds_read_b128 v[2:5], v98 offset:9216
	ds_read_b128 v[6:9], v98 offset:9472
	v_add_f32_dpp v104, v104, v104 quad_perm:[2,3,0,1] row_mask:0xf bank_mask:0xf bound_ctrl:1
	v_pk_mul_f32 v[36:37], v[36:37], v[40:41] op_sel_hi:[1,0]
	v_pk_mul_f32 v[38:39], v[38:39], v[40:41] op_sel_hi:[1,0]
	v_add_f32_dpp v104, v104, v104 row_half_mirror row_mask:0xf bank_mask:0xf bound_ctrl:1
	s_waitcnt lgkmcnt(5)
	v_pk_fma_f32 v[36:37], v[100:101], v[28:29], v[36:37]
	v_pk_fma_f32 v[38:39], v[102:103], v[30:31], v[38:39]
	v_add_f32_dpp v104, v104, v104 row_mirror row_mask:0xf bank_mask:0xf bound_ctrl:1
	v_pk_fma_f32 v[100:101], v[32:33], v[104:105], v[36:37] op_sel_hi:[1,0,1] neg_lo:[0,1,0] neg_hi:[0,1,0]
	v_pk_fma_f32 v[102:103], v[34:35], v[104:105], v[38:39] op_sel_hi:[1,0,1] neg_lo:[0,1,0] neg_hi:[0,1,0]
	v_pk_mul_f32 v[106:107], v[100:101], v[84:85]
	ds_read_b128 v[10:13], v98 offset:9728
	v_pk_fma_f32 v[106:107], v[102:103], v[86:87], v[106:107]
	s_waitcnt lgkmcnt(2)
	v_pk_mul_f32 v[104:105], v[100:101], v[2:3]
	v_add_f32_e32 v106, v106, v107
	ds_read_b128 v[18:21], v98 offset:10240
	v_pk_fma_f32 v[104:105], v[102:103], v[4:5], v[104:105]
	v_add_f32_dpp v106, v106, v106 quad_perm:[1,0,3,2] row_mask:0xf bank_mask:0xf bound_ctrl:1
	v_add_f32_e32 v104, v104, v105
	s_nop 0
	v_add_f32_dpp v106, v106, v106 quad_perm:[2,3,0,1] row_mask:0xf bank_mask:0xf bound_ctrl:1
	ds_write_b32 v97, v106 offset:1280
	ds_read_b32 v40, v99 offset:12032
	ds_read_b128 v[36:39], v98 offset:11520
	v_add_f32_dpp v104, v104, v104 quad_perm:[1,0,3,2] row_mask:0xf bank_mask:0xf bound_ctrl:1
	ds_read_b128 v[24:27], v98 offset:10752
	ds_read_b128 v[28:31], v98 offset:11008
	v_add_f32_dpp v104, v104, v104 quad_perm:[2,3,0,1] row_mask:0xf bank_mask:0xf bound_ctrl:1
	v_pk_mul_f32 v[14:15], v[14:15], v[22:23] op_sel_hi:[1,0]
	v_pk_mul_f32 v[16:17], v[16:17], v[22:23] op_sel_hi:[1,0]
	v_add_f32_dpp v104, v104, v104 row_half_mirror row_mask:0xf bank_mask:0xf bound_ctrl:1
	s_waitcnt lgkmcnt(5)
	v_pk_fma_f32 v[14:15], v[100:101], v[6:7], v[14:15]
	v_pk_fma_f32 v[16:17], v[102:103], v[8:9], v[16:17]
	v_add_f32_dpp v104, v104, v104 row_mirror row_mask:0xf bank_mask:0xf bound_ctrl:1
	v_pk_fma_f32 v[100:101], v[10:11], v[104:105], v[14:15] op_sel_hi:[1,0,1] neg_lo:[0,1,0] neg_hi:[0,1,0]
	v_pk_fma_f32 v[102:103], v[12:13], v[104:105], v[16:17] op_sel_hi:[1,0,1] neg_lo:[0,1,0] neg_hi:[0,1,0]
	v_pk_mul_f32 v[106:107], v[100:101], v[18:19]
	ds_read_b128 v[32:35], v98 offset:11264
	v_pk_fma_f32 v[106:107], v[102:103], v[20:21], v[106:107]
	s_waitcnt lgkmcnt(2)
; DEVI void rwkv_scan_item(const Params& p, const int item, char* smem) {
;     ...
; #pragma unroll 2
;       for (int s = 0; s < 32; s += 2) {
;         RW_LD(s + 1, B)
;         __builtin_amdgcn_sched_barrier(0);
;         RW_STEP(s, A)
;         __builtin_amdgcn_sched_barrier(0);
;         if (s + 2 < 32) RW_LD(s + 2, A)
;         __builtin_amdgcn_sched_barrier(0);
;         RW_STEP(s + 1, B)
;         __builtin_amdgcn_sched_barrier(0);
;       }
	v_pk_mul_f32 v[104:105], v[100:101], v[24:25]
	v_add_f32_e32 v106, v106, v107
	ds_read_b128 v[84:87], v98 offset:11776
	v_pk_fma_f32 v[104:105], v[102:103], v[26:27], v[104:105]
	v_add_f32_dpp v106, v106, v106 quad_perm:[1,0,3,2] row_mask:0xf bank_mask:0xf bound_ctrl:1
	v_add_f32_e32 v104, v104, v105
	s_nop 0
	v_add_f32_dpp v106, v106, v106 quad_perm:[2,3,0,1] row_mask:0xf bank_mask:0xf bound_ctrl:1
	ds_write_b32 v97, v106 offset:1536
	ds_read_b32 v22, v99 offset:13568
	ds_read_b128 v[14:17], v98 offset:13056
	v_add_f32_dpp v104, v104, v104 quad_perm:[1,0,3,2] row_mask:0xf bank_mask:0xf bound_ctrl:1
	ds_read_b128 v[2:5], v98 offset:12288
	ds_read_b128 v[6:9], v98 offset:12544
	v_add_f32_dpp v104, v104, v104 quad_perm:[2,3,0,1] row_mask:0xf bank_mask:0xf bound_ctrl:1
	v_pk_mul_f32 v[36:37], v[36:37], v[40:41] op_sel_hi:[1,0]
	v_pk_mul_f32 v[38:39], v[38:39], v[40:41] op_sel_hi:[1,0]
	v_add_f32_dpp v104, v104, v104 row_half_mirror row_mask:0xf bank_mask:0xf bound_ctrl:1
	s_waitcnt lgkmcnt(5)
	v_pk_fma_f32 v[36:37], v[100:101], v[28:29], v[36:37]
	v_pk_fma_f32 v[38:39], v[102:103], v[30:31], v[38:39]
	v_add_f32_dpp v104, v104, v104 row_mirror row_mask:0xf bank_mask:0xf bound_ctrl:1
	v_pk_fma_f32 v[100:101], v[32:33], v[104:105], v[36:37] op_sel_hi:[1,0,1] neg_lo:[0,1,0] neg_hi:[0,1,0]
	v_pk_fma_f32 v[102:103], v[34:35], v[104:105], v[38:39] op_sel_hi:[1,0,1] neg_lo:[0,1,0] neg_hi:[0,1,0]
	v_pk_mul_f32 v[106:107], v[100:101], v[84:85]
	ds_read_b128 v[10:13], v98 offset:12800
	v_pk_fma_f32 v[106:107], v[102:103], v[86:87], v[106:107]
	s_waitcnt lgkmcnt(2)
	v_pk_mul_f32 v[104:105], v[100:101], v[2:3]
	v_add_f32_e32 v106, v106, v107
	ds_read_b128 v[18:21], v98 offset:13312
	v_pk_fma_f32 v[104:105], v[102:103], v[4:5], v[104:105]
	v_add_f32_dpp v106, v106, v106 quad_perm:[1,0,3,2] row_mask:0xf bank_mask:0xf bound_ctrl:1
	v_add_f32_e32 v104, v104, v105
	s_nop 0
	v_add_f32_dpp v106, v106, v106 quad_perm:[2,3,0,1] row_mask:0xf bank_mask:0xf bound_ctrl:1
	ds_write_b32 v97, v106 offset:1792
	ds_read_b32 v40, v99 offset:15104
	ds_read_b128 v[36:39], v98 offset:14592
	v_add_f32_dpp v104, v104, v104 quad_perm:[1,0,3,2] row_mask:0xf bank_mask:0xf bound_ctrl:1
	ds_read_b128 v[24:27], v98 offset:13824
	ds_read_b128 v[28:31], v98 offset:14080
	v_add_f32_dpp v104, v104, v104 quad_perm:[2,3,0,1] row_mask:0xf bank_mask:0xf bound_ctrl:1
	v_pk_mul_f32 v[14:15], v[14:15], v[22:23] op_sel_hi:[1,0]
	v_pk_mul_f32 v[16:17], v[16:17], v[22:23] op_sel_hi:[1,0]
	v_add_f32_dpp v104, v104, v104 row_half_mirror row_mask:0xf bank_mask:0xf bound_ctrl:1
	s_waitcnt lgkmcnt(5)
	v_pk_fma_f32 v[14:15], v[100:101], v[6:7], v[14:15]
	v_pk_fma_f32 v[16:17], v[102:103], v[8:9], v[16:17]
	v_add_f32_dpp v104, v104, v104 row_mirror row_mask:0xf bank_mask:0xf bound_ctrl:1
	v_pk_fma_f32 v[100:101], v[10:11], v[104:105], v[14:15] op_sel_hi:[1,0,1] neg_lo:[0,1,0] neg_hi:[0,1,0]
	v_pk_fma_f32 v[102:103], v[12:13], v[104:105], v[16:17] op_sel_hi:[1,0,1] neg_lo:[0,1,0] neg_hi:[0,1,0]
	v_pk_mul_f32 v[106:107], v[100:101], v[18:19]
	ds_read_b128 v[32:35], v98 offset:14336
	v_pk_fma_f32 v[106:107], v[102:103], v[20:21], v[106:107]
	s_waitcnt lgkmcnt(2)
	v_pk_mul_f32 v[104:105], v[100:101], v[24:25]
	v_add_f32_e32 v106, v106, v107
	ds_read_b128 v[84:87], v98 offset:14848
	v_pk_fma_f32 v[104:105], v[102:103], v[26:27], v[104:105]
	v_add_f32_dpp v106, v106, v106 quad_perm:[1,0,3,2] row_mask:0xf bank_mask:0xf bound_ctrl:1
	v_add_f32_e32 v104, v104, v105
	s_nop 0
	v_add_f32_dpp v106, v106, v106 quad_perm:[2,3,0,1] row_mask:0xf bank_mask:0xf bound_ctrl:1
	ds_write_b32 v97, v106 offset:2048
	ds_read_b32 v22, v99 offset:16640
	ds_read_b128 v[14:17], v98 offset:16128
	v_add_f32_dpp v104, v104, v104 quad_perm:[1,0,3,2] row_mask:0xf bank_mask:0xf bound_ctrl:1
	ds_read_b128 v[2:5], v98 offset:15360
	ds_read_b128 v[6:9], v98 offset:15616
	v_add_f32_dpp v104, v104, v104 quad_perm:[2,3,0,1] row_mask:0xf bank_mask:0xf bound_ctrl:1
	v_pk_mul_f32 v[36:37], v[36:37], v[40:41] op_sel_hi:[1,0]
	v_pk_mul_f32 v[38:39], v[38:39], v[40:41] op_sel_hi:[1,0]
	v_add_f32_dpp v104, v104, v104 row_half_mirror row_mask:0xf bank_mask:0xf bound_ctrl:1
	s_waitcnt lgkmcnt(5)
	v_pk_fma_f32 v[36:37], v[100:101], v[28:29], v[36:37]
	v_pk_fma_f32 v[38:39], v[102:103], v[30:31], v[38:39]
	v_add_f32_dpp v104, v104, v104 row_mirror row_mask:0xf bank_mask:0xf bound_ctrl:1
	v_pk_fma_f32 v[100:101], v[32:33], v[104:105], v[36:37] op_sel_hi:[1,0,1] neg_lo:[0,1,0] neg_hi:[0,1,0]
	v_pk_fma_f32 v[102:103], v[34:35], v[104:105], v[38:39] op_sel_hi:[1,0,1] neg_lo:[0,1,0] neg_hi:[0,1,0]
	v_pk_mul_f32 v[106:107], v[100:101], v[84:85]
	ds_read_b128 v[10:13], v98 offset:15872
	v_pk_fma_f32 v[106:107], v[102:103], v[86:87], v[106:107]
	s_waitcnt lgkmcnt(2)
	v_pk_mul_f32 v[104:105], v[100:101], v[2:3]
	v_add_f32_e32 v106, v106, v107
	ds_read_b128 v[18:21], v98 offset:16384
	v_pk_fma_f32 v[104:105], v[102:103], v[4:5], v[104:105]
	v_add_f32_dpp v106, v106, v106 quad_perm:[1,0,3,2] row_mask:0xf bank_mask:0xf bound_ctrl:1
	v_add_f32_e32 v104, v104, v105
	s_nop 0
	v_add_f32_dpp v106, v106, v106 quad_perm:[2,3,0,1] row_mask:0xf bank_mask:0xf bound_ctrl:1
	ds_write_b32 v97, v106 offset:2304
	ds_read_b32 v40, v99 offset:18176
	ds_read_b128 v[36:39], v98 offset:17664
	v_add_f32_dpp v104, v104, v104 quad_perm:[1,0,3,2] row_mask:0xf bank_mask:0xf bound_ctrl:1
	ds_read_b128 v[24:27], v98 offset:16896
	ds_read_b128 v[28:31], v98 offset:17152
	v_add_f32_dpp v104, v104, v104 quad_perm:[2,3,0,1] row_mask:0xf bank_mask:0xf bound_ctrl:1
	v_pk_mul_f32 v[14:15], v[14:15], v[22:23] op_sel_hi:[1,0]
	v_pk_mul_f32 v[16:17], v[16:17], v[22:23] op_sel_hi:[1,0]
	v_add_f32_dpp v104, v104, v104 row_half_mirror row_mask:0xf bank_mask:0xf bound_ctrl:1
	s_waitcnt lgkmcnt(5)
; DEVI void rwkv_scan_item(const Params& p, const int item, char* smem) {
;     ...
; #pragma unroll 2
;       for (int s = 0; s < 32; s += 2) {
;         RW_LD(s + 1, B)
;         __builtin_amdgcn_sched_barrier(0);
;         RW_STEP(s, A)
;         __builtin_amdgcn_sched_barrier(0);
;         if (s + 2 < 32) RW_LD(s + 2, A)
;         __builtin_amdgcn_sched_barrier(0);
;         RW_STEP(s + 1, B)
;         __builtin_amdgcn_sched_barrier(0);
;       }
	v_pk_fma_f32 v[14:15], v[100:101], v[6:7], v[14:15]
	v_pk_fma_f32 v[16:17], v[102:103], v[8:9], v[16:17]
	v_add_f32_dpp v104, v104, v104 row_mirror row_mask:0xf bank_mask:0xf bound_ctrl:1
	v_pk_fma_f32 v[100:101], v[10:11], v[104:105], v[14:15] op_sel_hi:[1,0,1] neg_lo:[0,1,0] neg_hi:[0,1,0]
	v_pk_fma_f32 v[102:103], v[12:13], v[104:105], v[16:17] op_sel_hi:[1,0,1] neg_lo:[0,1,0] neg_hi:[0,1,0]
	v_pk_mul_f32 v[106:107], v[100:101], v[18:19]
	ds_read_b128 v[32:35], v98 offset:17408
	v_pk_fma_f32 v[106:107], v[102:103], v[20:21], v[106:107]
	s_waitcnt lgkmcnt(2)
	v_pk_mul_f32 v[104:105], v[100:101], v[24:25]
	v_add_f32_e32 v106, v106, v107
	ds_read_b128 v[84:87], v98 offset:17920
	v_pk_fma_f32 v[104:105], v[102:103], v[26:27], v[104:105]
	v_add_f32_dpp v106, v106, v106 quad_perm:[1,0,3,2] row_mask:0xf bank_mask:0xf bound_ctrl:1
	v_add_f32_e32 v104, v104, v105
	s_nop 0
	v_add_f32_dpp v106, v106, v106 quad_perm:[2,3,0,1] row_mask:0xf bank_mask:0xf bound_ctrl:1
	ds_write_b32 v97, v106 offset:2560
	ds_read_b32 v22, v99 offset:19712
	ds_read_b128 v[14:17], v98 offset:19200
	v_add_f32_dpp v104, v104, v104 quad_perm:[1,0,3,2] row_mask:0xf bank_mask:0xf bound_ctrl:1
	ds_read_b128 v[2:5], v98 offset:18432
	ds_read_b128 v[6:9], v98 offset:18688
	v_add_f32_dpp v104, v104, v104 quad_perm:[2,3,0,1] row_mask:0xf bank_mask:0xf bound_ctrl:1
	v_pk_mul_f32 v[36:37], v[36:37], v[40:41] op_sel_hi:[1,0]
	v_pk_mul_f32 v[38:39], v[38:39], v[40:41] op_sel_hi:[1,0]
	v_add_f32_dpp v104, v104, v104 row_half_mirror row_mask:0xf bank_mask:0xf bound_ctrl:1
	s_waitcnt lgkmcnt(5)
	v_pk_fma_f32 v[36:37], v[100:101], v[28:29], v[36:37]
	v_pk_fma_f32 v[38:39], v[102:103], v[30:31], v[38:39]
	v_add_f32_dpp v104, v104, v104 row_mirror row_mask:0xf bank_mask:0xf bound_ctrl:1
	v_pk_fma_f32 v[100:101], v[32:33], v[104:105], v[36:37] op_sel_hi:[1,0,1] neg_lo:[0,1,0] neg_hi:[0,1,0]
	v_pk_fma_f32 v[102:103], v[34:35], v[104:105], v[38:39] op_sel_hi:[1,0,1] neg_lo:[0,1,0] neg_hi:[0,1,0]
	v_pk_mul_f32 v[106:107], v[100:101], v[84:85]
	ds_read_b128 v[10:13], v98 offset:18944
	v_pk_fma_f32 v[106:107], v[102:103], v[86:87], v[106:107]
	s_waitcnt lgkmcnt(2)
	v_pk_mul_f32 v[104:105], v[100:101], v[2:3]
	v_add_f32_e32 v106, v106, v107
	ds_read_b128 v[18:21], v98 offset:19456
	v_pk_fma_f32 v[104:105], v[102:103], v[4:5], v[104:105]
	v_add_f32_dpp v106, v106, v106 quad_perm:[1,0,3,2] row_mask:0xf bank_mask:0xf bound_ctrl:1
	v_add_f32_e32 v104, v104, v105
	s_nop 0
	v_add_f32_dpp v106, v106, v106 quad_perm:[2,3,0,1] row_mask:0xf bank_mask:0xf bound_ctrl:1
	ds_write_b32 v97, v106 offset:2816
	ds_read_b32 v40, v99 offset:21248
	ds_read_b128 v[36:39], v98 offset:20736
	v_add_f32_dpp v104, v104, v104 quad_perm:[1,0,3,2] row_mask:0xf bank_mask:0xf bound_ctrl:1
	ds_read_b128 v[24:27], v98 offset:19968
	ds_read_b128 v[28:31], v98 offset:20224
	v_add_f32_dpp v104, v104, v104 quad_perm:[2,3,0,1] row_mask:0xf bank_mask:0xf bound_ctrl:1
	v_pk_mul_f32 v[14:15], v[14:15], v[22:23] op_sel_hi:[1,0]
	v_pk_mul_f32 v[16:17], v[16:17], v[22:23] op_sel_hi:[1,0]
	v_add_f32_dpp v104, v104, v104 row_half_mirror row_mask:0xf bank_mask:0xf bound_ctrl:1
	s_waitcnt lgkmcnt(5)
	v_pk_fma_f32 v[14:15], v[100:101], v[6:7], v[14:15]
	v_pk_fma_f32 v[16:17], v[102:103], v[8:9], v[16:17]
	v_add_f32_dpp v104, v104, v104 row_mirror row_mask:0xf bank_mask:0xf bound_ctrl:1
	v_pk_fma_f32 v[100:101], v[10:11], v[104:105], v[14:15] op_sel_hi:[1,0,1] neg_lo:[0,1,0] neg_hi:[0,1,0]
	v_pk_fma_f32 v[102:103], v[12:13], v[104:105], v[16:17] op_sel_hi:[1,0,1] neg_lo:[0,1,0] neg_hi:[0,1,0]
	v_pk_mul_f32 v[106:107], v[100:101], v[18:19]
	ds_read_b128 v[32:35], v98 offset:20480
	v_pk_fma_f32 v[106:107], v[102:103], v[20:21], v[106:107]
	s_waitcnt lgkmcnt(2)
	v_pk_mul_f32 v[104:105], v[100:101], v[24:25]
	v_add_f32_e32 v106, v106, v107
	ds_read_b128 v[84:87], v98 offset:20992
	v_pk_fma_f32 v[104:105], v[102:103], v[26:27], v[104:105]
	v_add_f32_dpp v106, v106, v106 quad_perm:[1,0,3,2] row_mask:0xf bank_mask:0xf bound_ctrl:1
	v_add_f32_e32 v104, v104, v105
	s_nop 0
	v_add_f32_dpp v106, v106, v106 quad_perm:[2,3,0,1] row_mask:0xf bank_mask:0xf bound_ctrl:1
	ds_write_b32 v97, v106 offset:3072
	ds_read_b32 v22, v99 offset:22784
	ds_read_b128 v[14:17], v98 offset:22272
	v_add_f32_dpp v104, v104, v104 quad_perm:[1,0,3,2] row_mask:0xf bank_mask:0xf bound_ctrl:1
	ds_read_b128 v[2:5], v98 offset:21504
	ds_read_b128 v[6:9], v98 offset:21760
	v_add_f32_dpp v104, v104, v104 quad_perm:[2,3,0,1] row_mask:0xf bank_mask:0xf bound_ctrl:1
	v_pk_mul_f32 v[36:37], v[36:37], v[40:41] op_sel_hi:[1,0]
	v_pk_mul_f32 v[38:39], v[38:39], v[40:41] op_sel_hi:[1,0]
	v_add_f32_dpp v104, v104, v104 row_half_mirror row_mask:0xf bank_mask:0xf bound_ctrl:1
	s_waitcnt lgkmcnt(5)
	v_pk_fma_f32 v[36:37], v[100:101], v[28:29], v[36:37]
	v_pk_fma_f32 v[38:39], v[102:103], v[30:31], v[38:39]
	v_add_f32_dpp v104, v104, v104 row_mirror row_mask:0xf bank_mask:0xf bound_ctrl:1
	v_pk_fma_f32 v[100:101], v[32:33], v[104:105], v[36:37] op_sel_hi:[1,0,1] neg_lo:[0,1,0] neg_hi:[0,1,0]
	v_pk_fma_f32 v[102:103], v[34:35], v[104:105], v[38:39] op_sel_hi:[1,0,1] neg_lo:[0,1,0] neg_hi:[0,1,0]
	v_pk_mul_f32 v[106:107], v[100:101], v[84:85]
	ds_read_b128 v[10:13], v98 offset:22016
	v_pk_fma_f32 v[106:107], v[102:103], v[86:87], v[106:107]
	s_waitcnt lgkmcnt(2)
; DEVI void rwkv_scan_item(const Params& p, const int item, char* smem) {
;     ...
; #pragma unroll 2
;       for (int s = 0; s < 32; s += 2) {
;         RW_LD(s + 1, B)
;         __builtin_amdgcn_sched_barrier(0);
;         RW_STEP(s, A)
;         __builtin_amdgcn_sched_barrier(0);
;         if (s + 2 < 32) RW_LD(s + 2, A)
;         __builtin_amdgcn_sched_barrier(0);
;         RW_STEP(s + 1, B)
;         __builtin_amdgcn_sched_barrier(0);
;       }
	v_pk_mul_f32 v[104:105], v[100:101], v[2:3]
	v_add_f32_e32 v106, v106, v107
	ds_read_b128 v[18:21], v98 offset:22528
	v_pk_fma_f32 v[104:105], v[102:103], v[4:5], v[104:105]
	v_add_f32_dpp v106, v106, v106 quad_perm:[1,0,3,2] row_mask:0xf bank_mask:0xf bound_ctrl:1
	v_add_f32_e32 v104, v104, v105
	s_nop 0
	v_add_f32_dpp v106, v106, v106 quad_perm:[2,3,0,1] row_mask:0xf bank_mask:0xf bound_ctrl:1
	ds_write_b32 v97, v106 offset:3328
	ds_read_b32 v40, v99 offset:24320
	ds_read_b128 v[36:39], v98 offset:23808
	v_add_f32_dpp v104, v104, v104 quad_perm:[1,0,3,2] row_mask:0xf bank_mask:0xf bound_ctrl:1
	ds_read_b128 v[24:27], v98 offset:23040
	ds_read_b128 v[28:31], v98 offset:23296
	v_add_f32_dpp v104, v104, v104 quad_perm:[2,3,0,1] row_mask:0xf bank_mask:0xf bound_ctrl:1
	v_pk_mul_f32 v[14:15], v[14:15], v[22:23] op_sel_hi:[1,0]
	v_pk_mul_f32 v[16:17], v[16:17], v[22:23] op_sel_hi:[1,0]
	v_add_f32_dpp v104, v104, v104 row_half_mirror row_mask:0xf bank_mask:0xf bound_ctrl:1
	s_waitcnt lgkmcnt(5)
	v_pk_fma_f32 v[14:15], v[100:101], v[6:7], v[14:15]
	v_pk_fma_f32 v[16:17], v[102:103], v[8:9], v[16:17]
	v_add_f32_dpp v104, v104, v104 row_mirror row_mask:0xf bank_mask:0xf bound_ctrl:1
	v_pk_fma_f32 v[100:101], v[10:11], v[104:105], v[14:15] op_sel_hi:[1,0,1] neg_lo:[0,1,0] neg_hi:[0,1,0]
	v_pk_fma_f32 v[102:103], v[12:13], v[104:105], v[16:17] op_sel_hi:[1,0,1] neg_lo:[0,1,0] neg_hi:[0,1,0]
	v_pk_mul_f32 v[106:107], v[100:101], v[18:19]
	ds_read_b128 v[32:35], v98 offset:23552
	v_pk_fma_f32 v[106:107], v[102:103], v[20:21], v[106:107]
	s_waitcnt lgkmcnt(2)
	v_pk_mul_f32 v[104:105], v[100:101], v[24:25]
	v_add_f32_e32 v106, v106, v107
	ds_read_b128 v[84:87], v98 offset:24064
	v_pk_fma_f32 v[104:105], v[102:103], v[26:27], v[104:105]
	v_add_f32_dpp v106, v106, v106 quad_perm:[1,0,3,2] row_mask:0xf bank_mask:0xf bound_ctrl:1
	v_add_f32_e32 v104, v104, v105
	s_nop 0
	v_add_f32_dpp v106, v106, v106 quad_perm:[2,3,0,1] row_mask:0xf bank_mask:0xf bound_ctrl:1
	ds_write_b32 v97, v106 offset:3584
	ds_read_b32 v22, v99 offset:25856
	ds_read_b128 v[14:17], v98 offset:25344
	v_add_f32_dpp v104, v104, v104 quad_perm:[1,0,3,2] row_mask:0xf bank_mask:0xf bound_ctrl:1
	ds_read_b128 v[2:5], v98 offset:24576
	ds_read_b128 v[6:9], v98 offset:24832
	v_add_f32_dpp v104, v104, v104 quad_perm:[2,3,0,1] row_mask:0xf bank_mask:0xf bound_ctrl:1
	v_pk_mul_f32 v[36:37], v[36:37], v[40:41] op_sel_hi:[1,0]
	v_pk_mul_f32 v[38:39], v[38:39], v[40:41] op_sel_hi:[1,0]
	v_add_f32_dpp v104, v104, v104 row_half_mirror row_mask:0xf bank_mask:0xf bound_ctrl:1
	s_waitcnt lgkmcnt(5)
	v_pk_fma_f32 v[36:37], v[100:101], v[28:29], v[36:37]
	v_pk_fma_f32 v[38:39], v[102:103], v[30:31], v[38:39]
	v_add_f32_dpp v104, v104, v104 row_mirror row_mask:0xf bank_mask:0xf bound_ctrl:1
	v_pk_fma_f32 v[100:101], v[32:33], v[104:105], v[36:37] op_sel_hi:[1,0,1] neg_lo:[0,1,0] neg_hi:[0,1,0]
	v_pk_fma_f32 v[102:103], v[34:35], v[104:105], v[38:39] op_sel_hi:[1,0,1] neg_lo:[0,1,0] neg_hi:[0,1,0]
	v_pk_mul_f32 v[106:107], v[100:101], v[84:85]
	ds_read_b128 v[10:13], v98 offset:25088
	v_pk_fma_f32 v[106:107], v[102:103], v[86:87], v[106:107]
	s_waitcnt lgkmcnt(2)
	v_pk_mul_f32 v[104:105], v[100:101], v[2:3]
	v_add_f32_e32 v106, v106, v107
	ds_read_b128 v[18:21], v98 offset:25600
	v_pk_fma_f32 v[104:105], v[102:103], v[4:5], v[104:105]
	v_add_f32_dpp v106, v106, v106 quad_perm:[1,0,3,2] row_mask:0xf bank_mask:0xf bound_ctrl:1
	v_add_f32_e32 v104, v104, v105
	s_nop 0
	v_add_f32_dpp v106, v106, v106 quad_perm:[2,3,0,1] row_mask:0xf bank_mask:0xf bound_ctrl:1
	ds_write_b32 v97, v106 offset:3840
	ds_read_b32 v40, v99 offset:27392
	ds_read_b128 v[36:39], v98 offset:26880
	v_add_f32_dpp v104, v104, v104 quad_perm:[1,0,3,2] row_mask:0xf bank_mask:0xf bound_ctrl:1
	ds_read_b128 v[24:27], v98 offset:26112
	ds_read_b128 v[28:31], v98 offset:26368
	v_add_f32_dpp v104, v104, v104 quad_perm:[2,3,0,1] row_mask:0xf bank_mask:0xf bound_ctrl:1
	v_pk_mul_f32 v[14:15], v[14:15], v[22:23] op_sel_hi:[1,0]
	v_pk_mul_f32 v[16:17], v[16:17], v[22:23] op_sel_hi:[1,0]
	v_add_f32_dpp v104, v104, v104 row_half_mirror row_mask:0xf bank_mask:0xf bound_ctrl:1
	s_waitcnt lgkmcnt(5)
	v_pk_fma_f32 v[14:15], v[100:101], v[6:7], v[14:15]
	v_pk_fma_f32 v[16:17], v[102:103], v[8:9], v[16:17]
	v_add_f32_dpp v104, v104, v104 row_mirror row_mask:0xf bank_mask:0xf bound_ctrl:1
	v_pk_fma_f32 v[100:101], v[10:11], v[104:105], v[14:15] op_sel_hi:[1,0,1] neg_lo:[0,1,0] neg_hi:[0,1,0]
	v_pk_fma_f32 v[102:103], v[12:13], v[104:105], v[16:17] op_sel_hi:[1,0,1] neg_lo:[0,1,0] neg_hi:[0,1,0]
	v_pk_mul_f32 v[106:107], v[100:101], v[18:19]
	ds_read_b128 v[32:35], v98 offset:26624
	v_pk_fma_f32 v[106:107], v[102:103], v[20:21], v[106:107]
	s_waitcnt lgkmcnt(2)
	v_pk_mul_f32 v[104:105], v[100:101], v[24:25]
	v_add_f32_e32 v106, v106, v107
	ds_read_b128 v[84:87], v98 offset:27136
	v_pk_fma_f32 v[104:105], v[102:103], v[26:27], v[104:105]
	v_add_f32_dpp v106, v106, v106 quad_perm:[1,0,3,2] row_mask:0xf bank_mask:0xf bound_ctrl:1
	v_add_f32_e32 v104, v104, v105
	s_nop 0
	v_add_f32_dpp v106, v106, v106 quad_perm:[2,3,0,1] row_mask:0xf bank_mask:0xf bound_ctrl:1
	ds_write_b32 v97, v106 offset:4096
	ds_read_b32 v22, v99 offset:28928
	ds_read_b128 v[14:17], v98 offset:28416
	v_add_f32_dpp v104, v104, v104 quad_perm:[1,0,3,2] row_mask:0xf bank_mask:0xf bound_ctrl:1
	ds_read_b128 v[2:5], v98 offset:27648
	ds_read_b128 v[6:9], v98 offset:27904
	v_add_f32_dpp v104, v104, v104 quad_perm:[2,3,0,1] row_mask:0xf bank_mask:0xf bound_ctrl:1
	v_pk_mul_f32 v[36:37], v[36:37], v[40:41] op_sel_hi:[1,0]
	v_pk_mul_f32 v[38:39], v[38:39], v[40:41] op_sel_hi:[1,0]
	v_add_f32_dpp v104, v104, v104 row_half_mirror row_mask:0xf bank_mask:0xf bound_ctrl:1
	s_waitcnt lgkmcnt(5)
; DEVI void rwkv_scan_item(const Params& p, const int item, char* smem) {
;     ...
; #pragma unroll 2
;       for (int s = 0; s < 32; s += 2) {
;         RW_LD(s + 1, B)
;         __builtin_amdgcn_sched_barrier(0);
;         RW_STEP(s, A)
;         __builtin_amdgcn_sched_barrier(0);
;         if (s + 2 < 32) RW_LD(s + 2, A)
;         __builtin_amdgcn_sched_barrier(0);
;         RW_STEP(s + 1, B)
;         __builtin_amdgcn_sched_barrier(0);
;       }
	v_pk_fma_f32 v[36:37], v[100:101], v[28:29], v[36:37]
	v_pk_fma_f32 v[38:39], v[102:103], v[30:31], v[38:39]
	v_add_f32_dpp v104, v104, v104 row_mirror row_mask:0xf bank_mask:0xf bound_ctrl:1
	v_pk_fma_f32 v[100:101], v[32:33], v[104:105], v[36:37] op_sel_hi:[1,0,1] neg_lo:[0,1,0] neg_hi:[0,1,0]
	v_pk_fma_f32 v[102:103], v[34:35], v[104:105], v[38:39] op_sel_hi:[1,0,1] neg_lo:[0,1,0] neg_hi:[0,1,0]
	v_pk_mul_f32 v[106:107], v[100:101], v[84:85]
	ds_read_b128 v[10:13], v98 offset:28160
	v_pk_fma_f32 v[106:107], v[102:103], v[86:87], v[106:107]
	s_waitcnt lgkmcnt(2)
	v_pk_mul_f32 v[104:105], v[100:101], v[2:3]
	v_add_f32_e32 v106, v106, v107
	ds_read_b128 v[18:21], v98 offset:28672
	v_pk_fma_f32 v[104:105], v[102:103], v[4:5], v[104:105]
	v_add_f32_dpp v106, v106, v106 quad_perm:[1,0,3,2] row_mask:0xf bank_mask:0xf bound_ctrl:1
	v_add_f32_e32 v104, v104, v105
	s_nop 0
	v_add_f32_dpp v106, v106, v106 quad_perm:[2,3,0,1] row_mask:0xf bank_mask:0xf bound_ctrl:1
	ds_write_b32 v97, v106 offset:4352
	ds_read_b32 v40, v99 offset:30464
	ds_read_b128 v[36:39], v98 offset:29952
	v_add_f32_dpp v104, v104, v104 quad_perm:[1,0,3,2] row_mask:0xf bank_mask:0xf bound_ctrl:1
	ds_read_b128 v[24:27], v98 offset:29184
	ds_read_b128 v[28:31], v98 offset:29440
	v_add_f32_dpp v104, v104, v104 quad_perm:[2,3,0,1] row_mask:0xf bank_mask:0xf bound_ctrl:1
	v_pk_mul_f32 v[14:15], v[14:15], v[22:23] op_sel_hi:[1,0]
	v_pk_mul_f32 v[16:17], v[16:17], v[22:23] op_sel_hi:[1,0]
	v_add_f32_dpp v104, v104, v104 row_half_mirror row_mask:0xf bank_mask:0xf bound_ctrl:1
	s_waitcnt lgkmcnt(5)
	v_pk_fma_f32 v[14:15], v[100:101], v[6:7], v[14:15]
	v_pk_fma_f32 v[16:17], v[102:103], v[8:9], v[16:17]
	v_add_f32_dpp v104, v104, v104 row_mirror row_mask:0xf bank_mask:0xf bound_ctrl:1
	v_pk_fma_f32 v[100:101], v[10:11], v[104:105], v[14:15] op_sel_hi:[1,0,1] neg_lo:[0,1,0] neg_hi:[0,1,0]
	v_pk_fma_f32 v[102:103], v[12:13], v[104:105], v[16:17] op_sel_hi:[1,0,1] neg_lo:[0,1,0] neg_hi:[0,1,0]
	v_pk_mul_f32 v[106:107], v[100:101], v[18:19]
	ds_read_b128 v[32:35], v98 offset:29696
	v_pk_fma_f32 v[106:107], v[102:103], v[20:21], v[106:107]
	s_waitcnt lgkmcnt(2)
	v_pk_mul_f32 v[104:105], v[100:101], v[24:25]
	v_add_f32_e32 v106, v106, v107
	ds_read_b128 v[84:87], v98 offset:30208
	v_pk_fma_f32 v[104:105], v[102:103], v[26:27], v[104:105]
	v_add_f32_dpp v106, v106, v106 quad_perm:[1,0,3,2] row_mask:0xf bank_mask:0xf bound_ctrl:1
	v_add_f32_e32 v104, v104, v105
	s_nop 0
	v_add_f32_dpp v106, v106, v106 quad_perm:[2,3,0,1] row_mask:0xf bank_mask:0xf bound_ctrl:1
	ds_write_b32 v97, v106 offset:4608
	ds_read_b32 v22, v99 offset:32000
	ds_read_b128 v[14:17], v98 offset:31488
	v_add_f32_dpp v104, v104, v104 quad_perm:[1,0,3,2] row_mask:0xf bank_mask:0xf bound_ctrl:1
	ds_read_b128 v[2:5], v98 offset:30720
	ds_read_b128 v[6:9], v98 offset:30976
	v_add_f32_dpp v104, v104, v104 quad_perm:[2,3,0,1] row_mask:0xf bank_mask:0xf bound_ctrl:1
	v_pk_mul_f32 v[36:37], v[36:37], v[40:41] op_sel_hi:[1,0]
	v_pk_mul_f32 v[38:39], v[38:39], v[40:41] op_sel_hi:[1,0]
	v_add_f32_dpp v104, v104, v104 row_half_mirror row_mask:0xf bank_mask:0xf bound_ctrl:1
	s_waitcnt lgkmcnt(5)
	v_pk_fma_f32 v[36:37], v[100:101], v[28:29], v[36:37]
	v_pk_fma_f32 v[38:39], v[102:103], v[30:31], v[38:39]
	v_add_f32_dpp v104, v104, v104 row_mirror row_mask:0xf bank_mask:0xf bound_ctrl:1
	v_pk_fma_f32 v[100:101], v[32:33], v[104:105], v[36:37] op_sel_hi:[1,0,1] neg_lo:[0,1,0] neg_hi:[0,1,0]
	v_pk_fma_f32 v[102:103], v[34:35], v[104:105], v[38:39] op_sel_hi:[1,0,1] neg_lo:[0,1,0] neg_hi:[0,1,0]
	v_pk_mul_f32 v[106:107], v[100:101], v[84:85]
	ds_read_b128 v[10:13], v98 offset:31232
	v_pk_fma_f32 v[106:107], v[102:103], v[86:87], v[106:107]
	s_waitcnt lgkmcnt(2)
	v_pk_mul_f32 v[104:105], v[100:101], v[2:3]
	v_add_f32_e32 v106, v106, v107
	ds_read_b128 v[18:21], v98 offset:31744
	v_pk_fma_f32 v[104:105], v[102:103], v[4:5], v[104:105]
	v_add_f32_dpp v106, v106, v106 quad_perm:[1,0,3,2] row_mask:0xf bank_mask:0xf bound_ctrl:1
	v_add_f32_e32 v104, v104, v105
	s_nop 0
	v_add_f32_dpp v106, v106, v106 quad_perm:[2,3,0,1] row_mask:0xf bank_mask:0xf bound_ctrl:1
	ds_write_b32 v97, v106 offset:4864
	ds_read_b32 v40, v99 offset:33536
	ds_read_b128 v[36:39], v98 offset:33024
	v_add_f32_dpp v104, v104, v104 quad_perm:[1,0,3,2] row_mask:0xf bank_mask:0xf bound_ctrl:1
	ds_read_b128 v[24:27], v98 offset:32256
	ds_read_b128 v[28:31], v98 offset:32512
	v_add_f32_dpp v104, v104, v104 quad_perm:[2,3,0,1] row_mask:0xf bank_mask:0xf bound_ctrl:1
	v_pk_mul_f32 v[14:15], v[14:15], v[22:23] op_sel_hi:[1,0]
	v_pk_mul_f32 v[16:17], v[16:17], v[22:23] op_sel_hi:[1,0]
	v_add_f32_dpp v104, v104, v104 row_half_mirror row_mask:0xf bank_mask:0xf bound_ctrl:1
	s_waitcnt lgkmcnt(5)
	v_pk_fma_f32 v[14:15], v[100:101], v[6:7], v[14:15]
	v_pk_fma_f32 v[16:17], v[102:103], v[8:9], v[16:17]
	v_add_f32_dpp v104, v104, v104 row_mirror row_mask:0xf bank_mask:0xf bound_ctrl:1
	v_pk_fma_f32 v[100:101], v[10:11], v[104:105], v[14:15] op_sel_hi:[1,0,1] neg_lo:[0,1,0] neg_hi:[0,1,0]
	v_pk_fma_f32 v[102:103], v[12:13], v[104:105], v[16:17] op_sel_hi:[1,0,1] neg_lo:[0,1,0] neg_hi:[0,1,0]
	v_pk_mul_f32 v[106:107], v[100:101], v[18:19]
	ds_read_b128 v[32:35], v98 offset:32768
	v_pk_fma_f32 v[106:107], v[102:103], v[20:21], v[106:107]
	s_waitcnt lgkmcnt(2)
; DEVI void rwkv_scan_item(const Params& p, const int item, char* smem) {
;     ...
; #pragma unroll 2
;       for (int s = 0; s < 32; s += 2) {
;         RW_LD(s + 1, B)
;         __builtin_amdgcn_sched_barrier(0);
;         RW_STEP(s, A)
;         __builtin_amdgcn_sched_barrier(0);
;         if (s + 2 < 32) RW_LD(s + 2, A)
;         __builtin_amdgcn_sched_barrier(0);
;         RW_STEP(s + 1, B)
;         __builtin_amdgcn_sched_barrier(0);
;       }
	v_pk_mul_f32 v[104:105], v[100:101], v[24:25]
	v_add_f32_e32 v106, v106, v107
	ds_read_b128 v[84:87], v98 offset:33280
	v_pk_fma_f32 v[104:105], v[102:103], v[26:27], v[104:105]
	v_add_f32_dpp v106, v106, v106 quad_perm:[1,0,3,2] row_mask:0xf bank_mask:0xf bound_ctrl:1
	v_add_f32_e32 v104, v104, v105
	s_nop 0
	v_add_f32_dpp v106, v106, v106 quad_perm:[2,3,0,1] row_mask:0xf bank_mask:0xf bound_ctrl:1
	ds_write_b32 v97, v106 offset:5120
	ds_read_b32 v22, v99 offset:35072
	ds_read_b128 v[14:17], v98 offset:34560
	v_add_f32_dpp v104, v104, v104 quad_perm:[1,0,3,2] row_mask:0xf bank_mask:0xf bound_ctrl:1
	ds_read_b128 v[2:5], v98 offset:33792
	ds_read_b128 v[6:9], v98 offset:34048
	v_add_f32_dpp v104, v104, v104 quad_perm:[2,3,0,1] row_mask:0xf bank_mask:0xf bound_ctrl:1
	v_pk_mul_f32 v[36:37], v[36:37], v[40:41] op_sel_hi:[1,0]
	v_pk_mul_f32 v[38:39], v[38:39], v[40:41] op_sel_hi:[1,0]
	v_add_f32_dpp v104, v104, v104 row_half_mirror row_mask:0xf bank_mask:0xf bound_ctrl:1
	s_waitcnt lgkmcnt(5)
	v_pk_fma_f32 v[36:37], v[100:101], v[28:29], v[36:37]
	v_pk_fma_f32 v[38:39], v[102:103], v[30:31], v[38:39]
	v_add_f32_dpp v104, v104, v104 row_mirror row_mask:0xf bank_mask:0xf bound_ctrl:1
	v_pk_fma_f32 v[100:101], v[32:33], v[104:105], v[36:37] op_sel_hi:[1,0,1] neg_lo:[0,1,0] neg_hi:[0,1,0]
	v_pk_fma_f32 v[102:103], v[34:35], v[104:105], v[38:39] op_sel_hi:[1,0,1] neg_lo:[0,1,0] neg_hi:[0,1,0]
	v_pk_mul_f32 v[106:107], v[100:101], v[84:85]
	ds_read_b128 v[10:13], v98 offset:34304
	v_pk_fma_f32 v[106:107], v[102:103], v[86:87], v[106:107]
	s_waitcnt lgkmcnt(2)
	v_pk_mul_f32 v[104:105], v[100:101], v[2:3]
	v_add_f32_e32 v106, v106, v107
	ds_read_b128 v[18:21], v98 offset:34816
	v_pk_fma_f32 v[104:105], v[102:103], v[4:5], v[104:105]
	v_add_f32_dpp v106, v106, v106 quad_perm:[1,0,3,2] row_mask:0xf bank_mask:0xf bound_ctrl:1
	v_add_f32_e32 v104, v104, v105
	s_nop 0
	v_add_f32_dpp v106, v106, v106 quad_perm:[2,3,0,1] row_mask:0xf bank_mask:0xf bound_ctrl:1
	ds_write_b32 v97, v106 offset:5376
	ds_read_b32 v40, v99 offset:36608
	ds_read_b128 v[36:39], v98 offset:36096
	v_add_f32_dpp v104, v104, v104 quad_perm:[1,0,3,2] row_mask:0xf bank_mask:0xf bound_ctrl:1
	ds_read_b128 v[24:27], v98 offset:35328
	ds_read_b128 v[28:31], v98 offset:35584
	v_add_f32_dpp v104, v104, v104 quad_perm:[2,3,0,1] row_mask:0xf bank_mask:0xf bound_ctrl:1
	v_pk_mul_f32 v[14:15], v[14:15], v[22:23] op_sel_hi:[1,0]
	v_pk_mul_f32 v[16:17], v[16:17], v[22:23] op_sel_hi:[1,0]
	v_add_f32_dpp v104, v104, v104 row_half_mirror row_mask:0xf bank_mask:0xf bound_ctrl:1
	s_waitcnt lgkmcnt(5)
	v_pk_fma_f32 v[14:15], v[100:101], v[6:7], v[14:15]
	v_pk_fma_f32 v[16:17], v[102:103], v[8:9], v[16:17]
	v_add_f32_dpp v104, v104, v104 row_mirror row_mask:0xf bank_mask:0xf bound_ctrl:1
	v_pk_fma_f32 v[100:101], v[10:11], v[104:105], v[14:15] op_sel_hi:[1,0,1] neg_lo:[0,1,0] neg_hi:[0,1,0]
	v_pk_fma_f32 v[102:103], v[12:13], v[104:105], v[16:17] op_sel_hi:[1,0,1] neg_lo:[0,1,0] neg_hi:[0,1,0]
	v_pk_mul_f32 v[106:107], v[100:101], v[18:19]
	ds_read_b128 v[32:35], v98 offset:35840
	v_pk_fma_f32 v[106:107], v[102:103], v[20:21], v[106:107]
	s_waitcnt lgkmcnt(2)
	v_pk_mul_f32 v[104:105], v[100:101], v[24:25]
	v_add_f32_e32 v106, v106, v107
	ds_read_b128 v[84:87], v98 offset:36352
	v_pk_fma_f32 v[104:105], v[102:103], v[26:27], v[104:105]
	v_add_f32_dpp v106, v106, v106 quad_perm:[1,0,3,2] row_mask:0xf bank_mask:0xf bound_ctrl:1
	v_add_f32_e32 v104, v104, v105
	s_nop 0
	v_add_f32_dpp v106, v106, v106 quad_perm:[2,3,0,1] row_mask:0xf bank_mask:0xf bound_ctrl:1
	ds_write_b32 v97, v106 offset:5632
	ds_read_b32 v22, v99 offset:38144
	ds_read_b128 v[14:17], v98 offset:37632
	v_add_f32_dpp v104, v104, v104 quad_perm:[1,0,3,2] row_mask:0xf bank_mask:0xf bound_ctrl:1
	ds_read_b128 v[2:5], v98 offset:36864
	ds_read_b128 v[6:9], v98 offset:37120
	v_add_f32_dpp v104, v104, v104 quad_perm:[2,3,0,1] row_mask:0xf bank_mask:0xf bound_ctrl:1
	v_pk_mul_f32 v[36:37], v[36:37], v[40:41] op_sel_hi:[1,0]
	v_pk_mul_f32 v[38:39], v[38:39], v[40:41] op_sel_hi:[1,0]
	v_add_f32_dpp v104, v104, v104 row_half_mirror row_mask:0xf bank_mask:0xf bound_ctrl:1
	s_waitcnt lgkmcnt(5)
	v_pk_fma_f32 v[36:37], v[100:101], v[28:29], v[36:37]
	v_pk_fma_f32 v[38:39], v[102:103], v[30:31], v[38:39]
	v_add_f32_dpp v104, v104, v104 row_mirror row_mask:0xf bank_mask:0xf bound_ctrl:1
	v_pk_fma_f32 v[100:101], v[32:33], v[104:105], v[36:37] op_sel_hi:[1,0,1] neg_lo:[0,1,0] neg_hi:[0,1,0]
	v_pk_fma_f32 v[102:103], v[34:35], v[104:105], v[38:39] op_sel_hi:[1,0,1] neg_lo:[0,1,0] neg_hi:[0,1,0]
	v_pk_mul_f32 v[106:107], v[100:101], v[84:85]
	ds_read_b128 v[10:13], v98 offset:37376
	v_pk_fma_f32 v[106:107], v[102:103], v[86:87], v[106:107]
	s_waitcnt lgkmcnt(2)
	v_pk_mul_f32 v[104:105], v[100:101], v[2:3]
	v_add_f32_e32 v106, v106, v107
	ds_read_b128 v[18:21], v98 offset:37888
	v_pk_fma_f32 v[104:105], v[102:103], v[4:5], v[104:105]
	v_add_f32_dpp v106, v106, v106 quad_perm:[1,0,3,2] row_mask:0xf bank_mask:0xf bound_ctrl:1
	v_add_f32_e32 v104, v104, v105
	s_nop 0
	v_add_f32_dpp v106, v106, v106 quad_perm:[2,3,0,1] row_mask:0xf bank_mask:0xf bound_ctrl:1
	ds_write_b32 v97, v106 offset:5888
	ds_read_b32 v40, v99 offset:39680
	ds_read_b128 v[36:39], v98 offset:39168
	v_add_f32_dpp v104, v104, v104 quad_perm:[1,0,3,2] row_mask:0xf bank_mask:0xf bound_ctrl:1
	ds_read_b128 v[24:27], v98 offset:38400
	ds_read_b128 v[28:31], v98 offset:38656
	v_add_f32_dpp v104, v104, v104 quad_perm:[2,3,0,1] row_mask:0xf bank_mask:0xf bound_ctrl:1
	v_pk_mul_f32 v[14:15], v[14:15], v[22:23] op_sel_hi:[1,0]
	v_pk_mul_f32 v[16:17], v[16:17], v[22:23] op_sel_hi:[1,0]
	v_add_f32_dpp v104, v104, v104 row_half_mirror row_mask:0xf bank_mask:0xf bound_ctrl:1
	s_waitcnt lgkmcnt(5)
; DEVI void rwkv_scan_item(const Params& p, const int item, char* smem) {
;     ...
; #pragma unroll 2
;       for (int s = 0; s < 32; s += 2) {
;         RW_LD(s + 1, B)
;         __builtin_amdgcn_sched_barrier(0);
;         RW_STEP(s, A)
;         __builtin_amdgcn_sched_barrier(0);
;         if (s + 2 < 32) RW_LD(s + 2, A)
;         __builtin_amdgcn_sched_barrier(0);
;         RW_STEP(s + 1, B)
;         __builtin_amdgcn_sched_barrier(0);
;       }
	v_pk_fma_f32 v[14:15], v[100:101], v[6:7], v[14:15]
	v_pk_fma_f32 v[16:17], v[102:103], v[8:9], v[16:17]
	v_add_f32_dpp v104, v104, v104 row_mirror row_mask:0xf bank_mask:0xf bound_ctrl:1
	v_pk_fma_f32 v[100:101], v[10:11], v[104:105], v[14:15] op_sel_hi:[1,0,1] neg_lo:[0,1,0] neg_hi:[0,1,0]
	v_pk_fma_f32 v[102:103], v[12:13], v[104:105], v[16:17] op_sel_hi:[1,0,1] neg_lo:[0,1,0] neg_hi:[0,1,0]
	v_pk_mul_f32 v[106:107], v[100:101], v[18:19]
	ds_read_b128 v[32:35], v98 offset:38912
	v_pk_fma_f32 v[106:107], v[102:103], v[20:21], v[106:107]
	s_waitcnt lgkmcnt(2)
	v_pk_mul_f32 v[104:105], v[100:101], v[24:25]
	v_add_f32_e32 v106, v106, v107
	ds_read_b128 v[84:87], v98 offset:39424
	v_pk_fma_f32 v[104:105], v[102:103], v[26:27], v[104:105]
	v_add_f32_dpp v106, v106, v106 quad_perm:[1,0,3,2] row_mask:0xf bank_mask:0xf bound_ctrl:1
	v_add_f32_e32 v104, v104, v105
	s_nop 0
	v_add_f32_dpp v106, v106, v106 quad_perm:[2,3,0,1] row_mask:0xf bank_mask:0xf bound_ctrl:1
	ds_write_b32 v97, v106 offset:6144
	ds_read_b32 v22, v99 offset:41216
	ds_read_b128 v[14:17], v98 offset:40704
	v_add_f32_dpp v104, v104, v104 quad_perm:[1,0,3,2] row_mask:0xf bank_mask:0xf bound_ctrl:1
	ds_read_b128 v[2:5], v98 offset:39936
	ds_read_b128 v[6:9], v98 offset:40192
	v_add_f32_dpp v104, v104, v104 quad_perm:[2,3,0,1] row_mask:0xf bank_mask:0xf bound_ctrl:1
	v_pk_mul_f32 v[36:37], v[36:37], v[40:41] op_sel_hi:[1,0]
	v_pk_mul_f32 v[38:39], v[38:39], v[40:41] op_sel_hi:[1,0]
	v_add_f32_dpp v104, v104, v104 row_half_mirror row_mask:0xf bank_mask:0xf bound_ctrl:1
	s_waitcnt lgkmcnt(5)
	v_pk_fma_f32 v[36:37], v[100:101], v[28:29], v[36:37]
	v_pk_fma_f32 v[38:39], v[102:103], v[30:31], v[38:39]
	v_add_f32_dpp v104, v104, v104 row_mirror row_mask:0xf bank_mask:0xf bound_ctrl:1
	v_pk_fma_f32 v[100:101], v[32:33], v[104:105], v[36:37] op_sel_hi:[1,0,1] neg_lo:[0,1,0] neg_hi:[0,1,0]
	v_pk_fma_f32 v[102:103], v[34:35], v[104:105], v[38:39] op_sel_hi:[1,0,1] neg_lo:[0,1,0] neg_hi:[0,1,0]
	v_pk_mul_f32 v[106:107], v[100:101], v[84:85]
	ds_read_b128 v[10:13], v98 offset:40448
	v_pk_fma_f32 v[106:107], v[102:103], v[86:87], v[106:107]
	s_waitcnt lgkmcnt(2)
	v_pk_mul_f32 v[104:105], v[100:101], v[2:3]
	v_add_f32_e32 v106, v106, v107
	ds_read_b128 v[18:21], v98 offset:40960
	v_pk_fma_f32 v[104:105], v[102:103], v[4:5], v[104:105]
	v_add_f32_dpp v106, v106, v106 quad_perm:[1,0,3,2] row_mask:0xf bank_mask:0xf bound_ctrl:1
	v_add_f32_e32 v104, v104, v105
	s_nop 0
	v_add_f32_dpp v106, v106, v106 quad_perm:[2,3,0,1] row_mask:0xf bank_mask:0xf bound_ctrl:1
	ds_write_b32 v97, v106 offset:6400
	ds_read_b32 v40, v99 offset:42752
	ds_read_b128 v[36:39], v98 offset:42240
	v_add_f32_dpp v104, v104, v104 quad_perm:[1,0,3,2] row_mask:0xf bank_mask:0xf bound_ctrl:1
	ds_read_b128 v[24:27], v98 offset:41472
	ds_read_b128 v[28:31], v98 offset:41728
	v_add_f32_dpp v104, v104, v104 quad_perm:[2,3,0,1] row_mask:0xf bank_mask:0xf bound_ctrl:1
	v_pk_mul_f32 v[14:15], v[14:15], v[22:23] op_sel_hi:[1,0]
	v_pk_mul_f32 v[16:17], v[16:17], v[22:23] op_sel_hi:[1,0]
	v_add_f32_dpp v104, v104, v104 row_half_mirror row_mask:0xf bank_mask:0xf bound_ctrl:1
	s_waitcnt lgkmcnt(5)
	v_pk_fma_f32 v[14:15], v[100:101], v[6:7], v[14:15]
	v_pk_fma_f32 v[16:17], v[102:103], v[8:9], v[16:17]
	v_add_f32_dpp v104, v104, v104 row_mirror row_mask:0xf bank_mask:0xf bound_ctrl:1
	v_pk_fma_f32 v[100:101], v[10:11], v[104:105], v[14:15] op_sel_hi:[1,0,1] neg_lo:[0,1,0] neg_hi:[0,1,0]
	v_pk_fma_f32 v[102:103], v[12:13], v[104:105], v[16:17] op_sel_hi:[1,0,1] neg_lo:[0,1,0] neg_hi:[0,1,0]
	v_pk_mul_f32 v[106:107], v[100:101], v[18:19]
	ds_read_b128 v[32:35], v98 offset:41984
	v_pk_fma_f32 v[106:107], v[102:103], v[20:21], v[106:107]
	s_waitcnt lgkmcnt(2)
	v_pk_mul_f32 v[104:105], v[100:101], v[24:25]
	v_add_f32_e32 v106, v106, v107
	ds_read_b128 v[84:87], v98 offset:42496
	v_pk_fma_f32 v[104:105], v[102:103], v[26:27], v[104:105]
	v_add_f32_dpp v106, v106, v106 quad_perm:[1,0,3,2] row_mask:0xf bank_mask:0xf bound_ctrl:1
	v_add_f32_e32 v104, v104, v105
	s_nop 0
	v_add_f32_dpp v106, v106, v106 quad_perm:[2,3,0,1] row_mask:0xf bank_mask:0xf bound_ctrl:1
	ds_write_b32 v97, v106 offset:6656
	ds_read_b32 v22, v99 offset:44288
	ds_read_b128 v[14:17], v98 offset:43776
	v_add_f32_dpp v104, v104, v104 quad_perm:[1,0,3,2] row_mask:0xf bank_mask:0xf bound_ctrl:1
	ds_read_b128 v[2:5], v98 offset:43008
	ds_read_b128 v[6:9], v98 offset:43264
	v_add_f32_dpp v104, v104, v104 quad_perm:[2,3,0,1] row_mask:0xf bank_mask:0xf bound_ctrl:1
	v_pk_mul_f32 v[36:37], v[36:37], v[40:41] op_sel_hi:[1,0]
	v_pk_mul_f32 v[38:39], v[38:39], v[40:41] op_sel_hi:[1,0]
	v_add_f32_dpp v104, v104, v104 row_half_mirror row_mask:0xf bank_mask:0xf bound_ctrl:1
	s_waitcnt lgkmcnt(5)
	v_pk_fma_f32 v[36:37], v[100:101], v[28:29], v[36:37]
	v_pk_fma_f32 v[38:39], v[102:103], v[30:31], v[38:39]
	v_add_f32_dpp v104, v104, v104 row_mirror row_mask:0xf bank_mask:0xf bound_ctrl:1
	v_pk_fma_f32 v[100:101], v[32:33], v[104:105], v[36:37] op_sel_hi:[1,0,1] neg_lo:[0,1,0] neg_hi:[0,1,0]
	v_pk_fma_f32 v[102:103], v[34:35], v[104:105], v[38:39] op_sel_hi:[1,0,1] neg_lo:[0,1,0] neg_hi:[0,1,0]
	v_pk_mul_f32 v[106:107], v[100:101], v[84:85]
	ds_read_b128 v[10:13], v98 offset:43520
	v_pk_fma_f32 v[106:107], v[102:103], v[86:87], v[106:107]
	s_waitcnt lgkmcnt(2)
; DEVI void rwkv_scan_item(const Params& p, const int item, char* smem) {
;     ...
; #pragma unroll 2
;       for (int s = 0; s < 32; s += 2) {
;         RW_LD(s + 1, B)
;         __builtin_amdgcn_sched_barrier(0);
;         RW_STEP(s, A)
;         __builtin_amdgcn_sched_barrier(0);
;         if (s + 2 < 32) RW_LD(s + 2, A)
;         __builtin_amdgcn_sched_barrier(0);
;         RW_STEP(s + 1, B)
;         __builtin_amdgcn_sched_barrier(0);
;       }
	v_pk_mul_f32 v[104:105], v[100:101], v[2:3]
	v_add_f32_e32 v106, v106, v107
	ds_read_b128 v[18:21], v98 offset:44032
	v_pk_fma_f32 v[104:105], v[102:103], v[4:5], v[104:105]
	v_add_f32_dpp v106, v106, v106 quad_perm:[1,0,3,2] row_mask:0xf bank_mask:0xf bound_ctrl:1
	v_add_f32_e32 v104, v104, v105
	s_nop 0
	v_add_f32_dpp v106, v106, v106 quad_perm:[2,3,0,1] row_mask:0xf bank_mask:0xf bound_ctrl:1
	ds_write_b32 v97, v106 offset:6912
	ds_read_b32 v40, v99 offset:45824
	ds_read_b128 v[36:39], v98 offset:45312
	v_add_f32_dpp v104, v104, v104 quad_perm:[1,0,3,2] row_mask:0xf bank_mask:0xf bound_ctrl:1
	ds_read_b128 v[24:27], v98 offset:44544
	ds_read_b128 v[28:31], v98 offset:44800
	v_add_f32_dpp v104, v104, v104 quad_perm:[2,3,0,1] row_mask:0xf bank_mask:0xf bound_ctrl:1
	v_pk_mul_f32 v[14:15], v[14:15], v[22:23] op_sel_hi:[1,0]
	v_pk_mul_f32 v[16:17], v[16:17], v[22:23] op_sel_hi:[1,0]
	v_add_f32_dpp v104, v104, v104 row_half_mirror row_mask:0xf bank_mask:0xf bound_ctrl:1
	s_waitcnt lgkmcnt(5)
	v_pk_fma_f32 v[14:15], v[100:101], v[6:7], v[14:15]
	v_pk_fma_f32 v[16:17], v[102:103], v[8:9], v[16:17]
	v_add_f32_dpp v104, v104, v104 row_mirror row_mask:0xf bank_mask:0xf bound_ctrl:1
	v_pk_fma_f32 v[100:101], v[10:11], v[104:105], v[14:15] op_sel_hi:[1,0,1] neg_lo:[0,1,0] neg_hi:[0,1,0]
	v_pk_fma_f32 v[102:103], v[12:13], v[104:105], v[16:17] op_sel_hi:[1,0,1] neg_lo:[0,1,0] neg_hi:[0,1,0]
	v_pk_mul_f32 v[106:107], v[100:101], v[18:19]
	ds_read_b128 v[32:35], v98 offset:45056
	v_pk_fma_f32 v[106:107], v[102:103], v[20:21], v[106:107]
	s_waitcnt lgkmcnt(2)
	v_pk_mul_f32 v[104:105], v[100:101], v[24:25]
	v_add_f32_e32 v106, v106, v107
	ds_read_b128 v[84:87], v98 offset:45568
	v_pk_fma_f32 v[104:105], v[102:103], v[26:27], v[104:105]
	v_add_f32_dpp v106, v106, v106 quad_perm:[1,0,3,2] row_mask:0xf bank_mask:0xf bound_ctrl:1
	v_add_f32_e32 v104, v104, v105
	s_nop 0
	v_add_f32_dpp v106, v106, v106 quad_perm:[2,3,0,1] row_mask:0xf bank_mask:0xf bound_ctrl:1
	ds_write_b32 v97, v106 offset:7168
	ds_read_b32 v22, v99 offset:47360
	ds_read_b128 v[14:17], v98 offset:46848
	v_add_f32_dpp v104, v104, v104 quad_perm:[1,0,3,2] row_mask:0xf bank_mask:0xf bound_ctrl:1
	ds_read_b128 v[2:5], v98 offset:46080
	ds_read_b128 v[6:9], v98 offset:46336
	v_add_f32_dpp v104, v104, v104 quad_perm:[2,3,0,1] row_mask:0xf bank_mask:0xf bound_ctrl:1
	v_pk_mul_f32 v[36:37], v[36:37], v[40:41] op_sel_hi:[1,0]
	v_pk_mul_f32 v[38:39], v[38:39], v[40:41] op_sel_hi:[1,0]
	v_add_f32_dpp v104, v104, v104 row_half_mirror row_mask:0xf bank_mask:0xf bound_ctrl:1
	s_waitcnt lgkmcnt(5)
	v_pk_fma_f32 v[36:37], v[100:101], v[28:29], v[36:37]
	v_pk_fma_f32 v[38:39], v[102:103], v[30:31], v[38:39]
	v_add_f32_dpp v104, v104, v104 row_mirror row_mask:0xf bank_mask:0xf bound_ctrl:1
	v_pk_fma_f32 v[100:101], v[32:33], v[104:105], v[36:37] op_sel_hi:[1,0,1] neg_lo:[0,1,0] neg_hi:[0,1,0]
	v_pk_fma_f32 v[102:103], v[34:35], v[104:105], v[38:39] op_sel_hi:[1,0,1] neg_lo:[0,1,0] neg_hi:[0,1,0]
	v_pk_mul_f32 v[106:107], v[100:101], v[84:85]
	ds_read_b128 v[10:13], v98 offset:46592
	v_pk_fma_f32 v[106:107], v[102:103], v[86:87], v[106:107]
	s_waitcnt lgkmcnt(2)
	v_pk_mul_f32 v[104:105], v[100:101], v[2:3]
	v_add_f32_e32 v106, v106, v107
	ds_read_b128 v[18:21], v98 offset:47104
	v_pk_fma_f32 v[104:105], v[102:103], v[4:5], v[104:105]
	v_add_f32_dpp v106, v106, v106 quad_perm:[1,0,3,2] row_mask:0xf bank_mask:0xf bound_ctrl:1
	v_add_f32_e32 v104, v104, v105
	s_nop 0
	v_add_f32_dpp v106, v106, v106 quad_perm:[2,3,0,1] row_mask:0xf bank_mask:0xf bound_ctrl:1
	ds_write_b32 v97, v106 offset:7424
	ds_read_b32 v40, v99 offset:48896
	ds_read_b128 v[36:39], v98 offset:48384
	v_add_f32_dpp v104, v104, v104 quad_perm:[1,0,3,2] row_mask:0xf bank_mask:0xf bound_ctrl:1
	ds_read_b128 v[24:27], v98 offset:47616
	ds_read_b128 v[28:31], v98 offset:47872
	v_add_f32_dpp v104, v104, v104 quad_perm:[2,3,0,1] row_mask:0xf bank_mask:0xf bound_ctrl:1
	v_pk_mul_f32 v[14:15], v[14:15], v[22:23] op_sel_hi:[1,0]
	v_pk_mul_f32 v[16:17], v[16:17], v[22:23] op_sel_hi:[1,0]
	v_add_f32_dpp v104, v104, v104 row_half_mirror row_mask:0xf bank_mask:0xf bound_ctrl:1
	s_waitcnt lgkmcnt(5)
	v_pk_fma_f32 v[14:15], v[100:101], v[6:7], v[14:15]
	v_pk_fma_f32 v[16:17], v[102:103], v[8:9], v[16:17]
	v_add_f32_dpp v104, v104, v104 row_mirror row_mask:0xf bank_mask:0xf bound_ctrl:1
	v_pk_fma_f32 v[100:101], v[10:11], v[104:105], v[14:15] op_sel_hi:[1,0,1] neg_lo:[0,1,0] neg_hi:[0,1,0]
	v_pk_fma_f32 v[102:103], v[12:13], v[104:105], v[16:17] op_sel_hi:[1,0,1] neg_lo:[0,1,0] neg_hi:[0,1,0]
	v_pk_mul_f32 v[106:107], v[100:101], v[18:19]
	ds_read_b128 v[32:35], v98 offset:48128
	v_pk_fma_f32 v[106:107], v[102:103], v[20:21], v[106:107]
	s_waitcnt lgkmcnt(2)
	v_pk_mul_f32 v[104:105], v[100:101], v[24:25]
	v_add_f32_e32 v106, v106, v107
	ds_read_b128 v[84:87], v98 offset:48640
	v_pk_fma_f32 v[104:105], v[102:103], v[26:27], v[104:105]
	v_add_f32_dpp v106, v106, v106 quad_perm:[1,0,3,2] row_mask:0xf bank_mask:0xf bound_ctrl:1
	v_add_f32_e32 v104, v104, v105
	s_nop 0
	v_add_f32_dpp v106, v106, v106 quad_perm:[2,3,0,1] row_mask:0xf bank_mask:0xf bound_ctrl:1
	ds_write_b32 v97, v106 offset:7680
	v_add_f32_dpp v104, v104, v104 quad_perm:[1,0,3,2] row_mask:0xf bank_mask:0xf bound_ctrl:1
	v_pk_mul_f32 v[36:37], v[36:37], v[40:41] op_sel_hi:[1,0]
	v_pk_mul_f32 v[38:39], v[38:39], v[40:41] op_sel_hi:[1,0]
	v_add_f32_dpp v104, v104, v104 quad_perm:[2,3,0,1] row_mask:0xf bank_mask:0xf bound_ctrl:1
	s_waitcnt lgkmcnt(1)
	v_pk_fma_f32 v[36:37], v[100:101], v[28:29], v[36:37]
	v_pk_fma_f32 v[38:39], v[102:103], v[30:31], v[38:39]
	v_add_f32_dpp v104, v104, v104 row_half_mirror row_mask:0xf bank_mask:0xf bound_ctrl:1
	s_nop 1
	v_add_f32_dpp v104, v104, v104 row_mirror row_mask:0xf bank_mask:0xf bound_ctrl:1
	v_pk_fma_f32 v[100:101], v[32:33], v[104:105], v[36:37] op_sel_hi:[1,0,1] neg_lo:[0,1,0] neg_hi:[0,1,0]
	v_pk_fma_f32 v[102:103], v[34:35], v[104:105], v[38:39] op_sel_hi:[1,0,1] neg_lo:[0,1,0] neg_hi:[0,1,0]
	v_pk_mul_f32 v[106:107], v[100:101], v[84:85]
	s_nop 0
	v_pk_fma_f32 v[106:107], v[102:103], v[86:87], v[106:107]
	s_nop 0
	v_add_f32_e32 v106, v106, v107
	s_nop 1
	v_add_f32_dpp v106, v106, v106 quad_perm:[1,0,3,2] row_mask:0xf bank_mask:0xf bound_ctrl:1
	s_nop 1
	v_add_f32_dpp v106, v106, v106 quad_perm:[2,3,0,1] row_mask:0xf bank_mask:0xf bound_ctrl:1
	ds_write_b32 v97, v106 offset:7936

;     ...
;   if (cidx != 1 && cidx != 3) for (int it = blockIdx.x; it < 96; it += gridDim.x) rwkv_scan_item(p, it, smem);
;   if (cidx == 2) return;
;   float d1 = 0.f, d2 = 0.f;
;   for (int i = 0; i < 64; ++i) { d1 += p.in[25][l * 64 + i] * p.in[26][l * 64 + i]; d2 += p.in[27][l * 64 + i] * p.in[28][l * 64 + i]; }
.LBB0_1302:
	s_setprio 0
	v_mov_b32_e32 v4, 0
	v_readlane_b32 s12, v252, 0
	s_mov_b64 s[0:1], 0
	v_mov_b32_e32 v2, 0
	v_mov_b32_e32 v3, v4
	v_readlane_b32 s14, v252, 2
	v_readlane_b32 s15, v252, 3
	v_readlane_b32 s16, v252, 4
	v_readlane_b32 s17, v252, 5
	v_readlane_b32 s18, v252, 6
	v_readlane_b32 s19, v252, 7
	v_readlane_b32 s20, v252, 8
	v_readlane_b32 s21, v252, 9
	v_readlane_b32 s22, v252, 10
	v_readlane_b32 s23, v252, 11
	v_readlane_b32 s13, v252, 1
	v_readlane_b32 s24, v252, 12
	v_readlane_b32 s25, v252, 13
	v_readlane_b32 s26, v252, 14
	v_readlane_b32 s27, v252, 15
